# nt stores for the chunk-local M,N,Q,Y items; state pass rewritten as a loop with role-split waves (Y tiles from Q / H tiles from M); split 21:11
# speedup vs baseline: 1.0384x; 1.0184x over previous
.LBB0_268:
	s_add_u32 s48, s98, 0xd900000
	s_addc_u32 s49, s99, 0
	s_add_u32 s76, s98, 0xfb00000
	s_addc_u32 s77, s99, 0
	s_cmp_lt_i32 s4, 3
	s_cselect_b64 s[0:1], -1, 0
	s_cmp_gt_i32 s5, 2
	s_cselect_b64 s[2:3], -1, 0
	s_and_b64 s[0:1], s[0:1], s[2:3]
	s_andn2_b64 vcc, exec, s[0:1]
	s_cbranch_vccnz .LBB0_518
	v_readlane_b32 s2, v250, 3
	s_and_b32 s0, s2, 16
	s_bitcmp1_b32 s2, 4
	s_cselect_b64 s[4:5], -1, 0
	s_ashr_i32 s1, s2, 1
	s_and_b32 s1, s1, -16
	s_and_b32 s2, s2, 15
	v_writelane_b32 v250, s4, 16
	s_or_b32 s1, s1, s2
	v_mov_b32_e32 v1, v0
	v_writelane_b32 v250, s5, 17
	s_lshl_b32 s4, s1, 5
	s_or_b32 s5, s4, 21
	s_cmp_eq_u32 s0, 0
	v_writelane_b32 v250, s1, 18
	s_cselect_b64 s[0:1], -1, 0
	s_and_b64 s[2:3], s[0:1], exec
	s_cselect_b32 s33, s4, s5
	s_ashr_i32 s2, s33, 10
	s_ashr_i32 s3, s2, 31
	s_lshl_b32 s4, s33, 5
	s_lshl_b64 s[2:3], s[2:3], 12
	s_and_b32 s10, s4, 0xfc0
	s_or_b32 s2, s2, s10
	v_ashrrev_i32_e32 v8, 3, v1
	v_lshlrev_b32_e32 v2, 3, v1
	v_ashrrev_i32_e32 v9, 31, v8
	v_and_b32_e32 v7, 56, v2
	v_lshl_add_u64 v[2:3], s[2:3], 0, v[8:9]
	s_movk_i32 s6, 0x2600
	v_mov_b64_e32 v[4:5], s[64:65]
	v_mad_u64_u32 v[4:5], s[4:5], v2, s6, v[4:5]
	v_mov_b32_e32 v6, 0
	v_mad_i32_i24 v5, v3, s6, v5
	v_lshlrev_b32_e32 v46, 1, v7
	v_mov_b32_e32 v47, v6
	v_lshl_add_u64 v[26:27], v[4:5], 0, v[46:47]
	s_and_b32 s8, s33, 1
	s_lshl_b32 s8, s8, 7
	s_mov_b32 s9, 0
	v_lshl_add_u64 v[26:27], v[26:27], 0, s[8:9]
	v_add_co_u32_e32 v2, vcc, 0x1000, v26
	v_add_u32_e32 v7, s10, v8
	s_nop 0
	v_addc_co_u32_e32 v3, vcc, 0, v27, vcc
	global_load_dwordx4 v[2:5], v[2:3], off
	v_cmp_lt_i32_e64 s[6:7], 0, v7
	v_mov_b32_e32 v10, 0
	v_mov_b32_e32 v11, 0
	v_mov_b32_e32 v12, 0
	v_mov_b32_e32 v13, 0
	s_and_saveexec_b64 s[4:5], s[6:7]
	s_cbranch_execz .LBB0_271
	v_add_co_u32_e32 v8, vcc, 0xfffff000, v26
	s_nop 1
	v_addc_co_u32_e32 v9, vcc, -1, v27, vcc
	global_load_dwordx4 v[10:13], v[8:9], off offset:-1536

.LBB0_293:
	s_or_b64 exec, exec, s[4:5]
	v_and_b32_e32 v26, 64, v0
	s_and_b64 s[0:1], s[0:1], exec
	v_cmp_eq_u32_e32 vcc, 0, v26
	v_mov_b32_e32 v26, s69
	v_mov_b32_e32 v27, s67
	v_cndmask_b32_e32 v27, v26, v27, vcc
	v_mov_b32_e32 v26, s68
	v_mov_b32_e32 v28, s66
	s_movk_i32 s0, 0x100
	v_cndmask_b32_e32 v26, v26, v28, vcc
	v_cmp_gt_u32_e64 s[2:3], s0, v0
	v_mov_b32_e32 v28, 0x880
	v_mov_b32_e32 v46, 0x800
	v_lshrrev_b32_e32 v170, 1, v0
	v_and_b32_e32 v1, 63, v0
	v_writelane_b32 v250, s2, 21
	s_cselect_b32 s72, 21, 11
	s_add_u32 s88, s96, 0x2000000
	v_cndmask_b32_e64 v28, v28, v46, s[2:3]
	v_and_b32_e32 v46, 64, v170
	v_or3_b32 v28, v28, v46, v1
	v_lshlrev_b32_e32 v28, 2, v28
	v_lshl_add_u64 v[26:27], v[26:27], 0, v[28:29]
	global_load_dword v26, v[26:27], off
	s_addc_u32 s89, s97, 0
	s_add_i32 s0, 0, 0x24000
	s_lshl_b32 s55, s50, 4
	s_cmpk_gt_u32 s51, 0xff
	s_cselect_b64 s[4:5], -1, 0
	s_cmpk_lt_u32 s51, 0x100
	s_cselect_b64 vcc, -1, 0
	v_writelane_b32 v250, s3, 22
	s_and_b64 s[2:3], vcc, exec
	s_cselect_b32 s3, s45, s47
	s_cselect_b32 s2, s44, s46
	v_and_b32_e32 v110, 48, v0
	v_mov_b32_e32 v111, v29
	v_lshl_add_u32 v27, v0, 2, s0
	v_lshl_add_u64 v[112:113], s[2:3], 0, v[110:111]
	s_movk_i32 s2, 0x340
	v_cmp_gt_u32_e64 s[2:3], s2, v0
	v_bfe_u32 v171, v0, 4, 2
	s_mov_b32 s23, 0x1dc00
	v_writelane_b32 v250, s2, 23
	v_and_b32_e32 v166, 15, v0
	v_lshlrev_b32_e32 v173, 2, v171
	v_writelane_b32 v250, s3, 24
	s_mov_b32 s3, 0xd000
	s_cselect_b32 s2, 0, 0x4000
	s_cselect_b32 s22, s3, 0xf800
	v_or_b32_e32 v54, 16, v166
	v_or_b32_e32 v51, 32, v166
	v_bitop3_b32 v28, s50, v171, 3 bitop3:0x6c
	s_movk_i32 s73, 0xa0
	v_or_b32_e32 v49, 48, v1
	v_lshlrev_b32_e32 v48, 6, v28
	v_lshlrev_b32_e32 v28, 2, v166
	v_mul_u32_u24_e32 v46, 0xa0, v49
	v_lshlrev_b32_e32 v188, 2, v1
	v_and_b32_e32 v72, 4, v173
	v_lshrrev_b32_e32 v111, 3, v0
	v_or_b32_e32 v184, s55, v166
	v_mul_lo_u32 v185, v184, s73
	v_lshlrev_b32_e32 v172, 3, v171
	v_lshlrev_b32_e32 v61, 1, v166
	v_lshl_add_u32 v63, v166, 6, 0
	s_mov_b32 s1, 0
	v_and_or_b32 v176, s55, 48, v166
	v_or_b32_e32 v177, 0x200, v0
	v_or_b32_e32 v178, 0x400, v0
	v_or_b32_e32 v179, 0x600, v0
	v_mul_u32_u24_e32 v167, 0xa0, v166
	v_add_u32_e32 v205, 0x24800, v175
	v_lshrrev_b32_e32 v187, 6, v0
	v_add_u32_e32 v215, v63, v110
	v_mov_b32_e32 v220, 0x90
	v_mov_b32_e32 v138, 0
	s_waitcnt vmcnt(0)
	ds_write_b32 v27, v26
	v_and_b32_e32 v27, 7, v0
	v_lshl_add_u32 v180, v27, 5, s0
	s_mov_b32 s0, 0x8000
	s_cselect_b32 s0, s0, 0xa800
	s_add_i32 s0, s0, 0
	v_add_u32_e32 v181, s0, v110
	s_add_i32 s0, s2, 0
	v_lshl_add_u32 v47, v171, 10, s0
	s_lshl_b32 s0, s50, 8
	s_lshl_b32 s92, s50, 1
	s_add_i32 s0, s0, 0
	s_cmp_lt_u32 s51, 64
	s_cselect_b64 s[8:9], -1, 0
	s_cmpk_gt_u32 s51, 0x7f
	s_cselect_b64 s[10:11], -1, 0
	s_cmpk_gt_u32 s51, 0xbf
	s_cselect_b64 s[12:13], -1, 0
	s_cmpk_gt_u32 s51, 0x13f
	s_cselect_b64 s[14:15], -1, 0
	s_cmpk_gt_u32 s51, 0x17f
	s_cselect_b64 s[16:17], -1, 0
	s_cmpk_gt_u32 s51, 0x1bf
	s_cselect_b64 s[18:19], -1, 0
	s_cmpk_gt_u32 s51, 0x1ff
	v_writelane_b32 v250, s0, 25
	s_cselect_b64 s[20:21], -1, 0
	s_lshr_b32 s0, s51, 7
	s_cmp_eq_u32 s0, 2
	s_cselect_b64 s[2:3], -1, 0
	s_and_b64 s[6:7], s[2:3], exec
	s_cselect_b32 s6, s23, 0x20400
	s_cmp_lg_u32 s0, 1
	s_cselect_b32 s23, s6, 0x4000
	s_cmpk_lt_u32 s51, 0x80
	s_cselect_b64 s[24:25], -1, 0
	s_and_b64 s[6:7], s[24:25], exec
	s_cselect_b32 s6, 0, s23
	v_writelane_b32 v250, s24, 26
	s_or_b64 s[2:3], s[24:25], s[2:3]
	s_mov_b32 s7, 0x14800
	s_and_b64 s[2:3], s[2:3], exec
	s_cselect_b32 s7, s7, 0x12000
	s_bfe_u32 s54, s51, 0x10006
	s_bitcmp1_b32 s51, 6
	s_cselect_b64 s[2:3], -1, 0
	s_add_i32 s22, s22, 0
	v_writelane_b32 v250, s25, 27
	v_mov_b32_e32 v53, s22
	v_cmp_lt_u32_e64 s[22:23], v173, v166
	v_cmp_le_u32_e64 s[24:25], v173, v166
	s_add_i32 s7, s7, 0
	v_cndmask_b32_e64 v56, 0, 1, s[22:23]
	v_cndmask_b32_e64 v57, 0, 1, s[24:25]
	v_cndmask_b32_e32 v56, v57, v56, vcc
	v_and_b32_e32 v56, 1, v56
	v_cmp_eq_u32_e64 s[22:23], 1, v56
	v_or_b32_e32 v56, 17, v173
	v_cmp_lt_u32_e64 s[24:25], v56, v54
	v_cmp_le_u32_e64 s[26:27], v56, v54
	s_add_i32 s6, s6, 0
	v_cndmask_b32_e64 v56, 0, 1, s[24:25]
	v_cndmask_b32_e64 v57, 0, 1, s[26:27]
	v_cndmask_b32_e32 v56, v57, v56, vcc
	v_and_b32_e32 v56, 1, v56
	v_mov_b32_e32 v52, s7
	v_mov_b32_e32 v55, s6
	v_cmp_eq_u32_e64 s[6:7], 1, v56
	v_or_b32_e32 v56, 18, v173
	v_cmp_lt_u32_e64 s[26:27], v56, v54
	v_cmp_le_u32_e64 s[28:29], v56, v54
	v_writelane_b32 v250, s6, 28
	v_cndmask_b32_e64 v56, 0, 1, s[26:27]
	v_cndmask_b32_e64 v57, 0, 1, s[28:29]
	v_cndmask_b32_e32 v56, v57, v56, vcc
	v_and_b32_e32 v56, 1, v56
	v_writelane_b32 v250, s7, 29
	v_cmp_eq_u32_e64 s[6:7], 1, v56
	v_or_b32_e32 v56, 19, v173
	v_cmp_lt_u32_e64 s[28:29], v56, v54
	v_cmp_le_u32_e64 s[30:31], v56, v54
	v_writelane_b32 v250, s6, 30
	v_cndmask_b32_e64 v54, 0, 1, s[28:29]
	v_cndmask_b32_e64 v56, 0, 1, s[30:31]
	v_cndmask_b32_e32 v54, v56, v54, vcc
	v_and_b32_e32 v54, 1, v54
	v_writelane_b32 v250, s7, 31
	v_cmp_eq_u32_e64 s[6:7], 1, v54
	v_or_b32_e32 v54, 33, v173
	v_cmp_lt_u32_e64 s[30:31], v54, v51
	v_cmp_le_u32_e64 s[34:35], v54, v51
	v_writelane_b32 v250, s6, 32
	v_cndmask_b32_e64 v54, 0, 1, s[30:31]
	v_cndmask_b32_e64 v57, 0, 1, s[34:35]
	v_cndmask_b32_e32 v54, v57, v54, vcc
	v_and_b32_e32 v54, 1, v54
	v_writelane_b32 v250, s7, 33
	v_cmp_eq_u32_e64 s[6:7], 1, v54
	v_or_b32_e32 v54, 34, v173
	v_cmp_lt_u32_e64 s[34:35], v54, v51
	v_cmp_le_u32_e64 s[36:37], v54, v51
	v_writelane_b32 v250, s6, 34
	v_cndmask_b32_e64 v54, 0, 1, s[34:35]
	v_cndmask_b32_e64 v57, 0, 1, s[36:37]
	v_cndmask_b32_e32 v54, v57, v54, vcc
	v_and_b32_e32 v54, 1, v54
	v_writelane_b32 v250, s7, 35
	v_cmp_eq_u32_e64 s[6:7], 1, v54
	v_or_b32_e32 v54, 35, v173
	v_cmp_lt_u32_e64 s[36:37], v54, v51
	v_cmp_le_u32_e64 s[38:39], v54, v51
	v_writelane_b32 v250, s6, 36
	v_cndmask_b32_e64 v51, 0, 1, s[36:37]
	v_cndmask_b32_e64 v54, 0, 1, s[38:39]
	v_cndmask_b32_e32 v51, v54, v51, vcc
	v_and_b32_e32 v51, 1, v51
	v_add3_u32 v182, v47, v48, v28
	v_mad_u32_u24 v47, v166, s73, v52
	v_mad_u32_u24 v48, v166, s73, v53
	v_writelane_b32 v250, s7, 37
	v_cmp_eq_u32_e64 s[6:7], 1, v51
	v_mad_u32_u24 v51, v49, s73, v53
	v_mad_u32_u24 v53, v49, s73, v52
	v_cndmask_b32_e64 v52, 0, 1, vcc
	v_writelane_b32 v250, s6, 38
	v_or_b32_e32 v52, v173, v52
	v_mad_u32_u24 v183, v166, s73, v55
	v_writelane_b32 v250, s7, 39
	v_cmp_gt_u32_e64 s[6:7], v166, v52
	v_or_b32_e32 v52, 2, v173
	v_cmp_lt_u32_e64 s[40:41], v52, v166
	v_cmp_le_u32_e64 s[42:43], v52, v166
	v_writelane_b32 v250, s6, 40
	v_cndmask_b32_e64 v52, 0, 1, s[40:41]
	v_cndmask_b32_e64 v54, 0, 1, s[42:43]
	v_cndmask_b32_e32 v52, v54, v52, vcc
	v_and_b32_e32 v52, 1, v52
	v_writelane_b32 v250, s7, 41
	v_cmp_eq_u32_e64 s[6:7], 1, v52
	v_or_b32_e32 v52, 3, v173
	v_cmp_lt_u32_e64 s[42:43], v52, v166
	v_cmp_le_u32_e64 s[44:45], v52, v166
	v_writelane_b32 v250, s6, 42
	v_cndmask_b32_e64 v52, 0, 1, s[42:43]
	v_cndmask_b32_e64 v54, 0, 1, s[44:45]
	v_cndmask_b32_e32 v52, v54, v52, vcc
	v_and_b32_e32 v52, 1, v52
	v_writelane_b32 v250, s7, 43
	v_cmp_eq_u32_e64 s[6:7], 1, v52
	v_or_b32_e32 v52, 48, v173
	v_cmp_lt_u32_e64 s[44:45], v52, v49
	v_cmp_le_u32_e64 s[46:47], v52, v49
	v_mad_u32_u24 v189, v49, s73, v55
	v_cndmask_b32_e64 v54, 0, 1, s[44:45]
	v_cndmask_b32_e64 v55, 0, 1, s[46:47]
	v_cndmask_b32_e32 v54, v55, v54, vcc
	v_writelane_b32 v250, s6, 44
	v_and_b32_e32 v54, 1, v54
	s_mov_b32 s25, s50
	v_writelane_b32 v250, s7, 45
	v_cmp_eq_u32_e64 s[6:7], 1, v54
	v_or_b32_e32 v54, 49, v173
	v_cmp_lt_u32_e64 s[46:47], v54, v49
	v_cmp_le_u32_e64 s[48:49], v54, v49
	v_writelane_b32 v250, s6, 46
	v_cndmask_b32_e64 v54, 0, 1, s[46:47]
	v_cndmask_b32_e64 v55, 0, 1, s[48:49]
	v_cndmask_b32_e32 v54, v55, v54, vcc
	v_and_b32_e32 v54, 1, v54
	v_writelane_b32 v250, s7, 47
	v_cmp_eq_u32_e64 s[6:7], 1, v54
	v_or_b32_e32 v54, 50, v173
	v_cmp_lt_u32_e64 s[48:49], v54, v49
	s_mov_b32 s24, s51
	v_cmp_le_u32_e64 s[50:51], v54, v49
	v_cndmask_b32_e64 v54, 0, 1, s[48:49]
	v_writelane_b32 v250, s6, 48
	v_cndmask_b32_e64 v55, 0, 1, s[50:51]
	v_cndmask_b32_e32 v54, v55, v54, vcc
	v_and_b32_e32 v54, 1, v54
	v_writelane_b32 v250, s7, 49
	v_cmp_eq_u32_e64 s[6:7], 1, v54
	v_or_b32_e32 v54, 51, v173
	v_cmp_lt_u32_e64 s[50:51], v54, v49
	v_cmp_le_u32_e64 s[52:53], v54, v49
	v_writelane_b32 v250, s6, 50
	v_cndmask_b32_e64 v49, 0, 1, s[50:51]
	v_cndmask_b32_e64 v54, 0, 1, s[52:53]
	v_cndmask_b32_e32 v49, v54, v49, vcc
	v_and_b32_e32 v49, 1, v49
	v_writelane_b32 v250, s7, 51
	v_cmp_eq_u32_e64 s[6:7], 1, v49
	v_lshlrev_b32_e32 v49, 1, v52
	v_add_u32_e32 v57, 0, v28
	v_writelane_b32 v250, s6, 52
	v_lshl_or_b32 v52, s54, 5, v166
	v_mul_u32_u24_e32 v58, 0x90, v52
	v_writelane_b32 v250, s7, 53
	s_movk_i32 s7, 0x9c
	v_or_b32_e32 v52, 16, v52
	v_mad_u32_u24 v60, v166, s7, v57
	s_movk_i32 s7, 0x480
	v_mul_u32_u24_e32 v59, 0x90, v52
	v_mad_u32_u24 v52, v171, s7, 0
	s_and_b32 s7, s24, 0xffffffc0
	s_lshl_b32 s26, s0, 4
	v_add3_u32 v191, v52, s7, v28
	v_lshlrev_b32_e32 v28, 9, v171
	v_or_b32_e32 v168, s26, v166
	s_movk_i32 s6, 0x90
	v_writelane_b32 v250, s24, 54
	v_sub_u32_e32 v28, v52, v28
	v_lshl_add_u32 v62, s25, 5, v28
	v_writelane_b32 v250, s55, 55
	v_mul_lo_u32 v28, v168, s6
	s_add_i32 s6, 0, 0x20400
	s_add_i32 s93, 0, 0x1b800
	s_add_i32 s40, 0, 0x12000
	s_and_b32 s7, s92, 2
	s_add_i32 s24, 0, 0x1dc00
	v_add_u32_e32 v193, s6, v110
	s_add_i32 s6, s26, 64
	s_add_i32 s41, 0, 0x19400
	s_add_i32 s42, 0, 0x17000
	v_writelane_b32 v250, s25, 56
	s_bitcmp1_b32 s25, 0
	v_writelane_b32 v250, s26, 57
	v_or_b32_e32 v73, s26, v173
	s_movk_i32 s43, 0x120
	v_add_u32_e32 v66, s93, v28
	v_or_b32_e32 v52, s6, v166
	v_add_u32_e32 v68, s42, v28
	v_add_u32_e32 v69, s41, v28
	v_lshl_or_b32 v70, s7, 4, v166
	s_cselect_b64 s[62:63], -1, 0
	s_lshl_b32 s6, s7, 10
	v_lshl_or_b32 v169, s0, 8, v188
	s_or_b32 s0, s7, 1
	v_mul_lo_u32 v28, v73, s43
	v_writelane_b32 v250, s54, 58
	s_lshl_b32 s7, s54, 7
	v_add_u32_e32 v192, s24, v110
	s_add_i32 s24, 0, 0x22c00
	v_lshl_or_b32 v71, s0, 4, v166
	s_lshl_b32 s0, s0, 10
	v_add3_u32 v202, v57, v28, s7
	v_lshlrev_b32_e32 v28, 1, v73
	s_mov_b32 s7, 0x1ffffff0
	v_readlane_b32 s26, v250, 19
	v_and_or_b32 v57, v28, s7, v166
	v_readlane_b32 s27, v250, 20
	s_add_u32 s38, s66, 0x1000
	v_add_u32_e32 v203, 0, v28
	v_lshl_add_u64 v[118:119], s[26:27], 0, v[28:29]
	v_lshlrev_b32_e32 v28, 3, v57
	s_addc_u32 s39, s67, 0
	v_add_u32_e32 v114, s6, v169
	v_add_u32_e32 v57, s6, v28
	s_add_u32 s6, s68, 0x800
	s_addc_u32 s7, s69, 0
	v_or_b32_e32 v120, v57, v72
	v_or_b32_e32 v57, 1, v73
	v_cmp_eq_u32_e64 s[52:53], v73, v70
	v_add_u32_e32 v28, s0, v28
	v_writelane_b32 v250, s6, 59
	v_cmp_eq_u32_e32 vcc, v57, v70
	v_cndmask_b32_e64 v122, 0, 1.0, s[52:53]
	v_or_b32_e32 v124, v28, v72
	v_cmp_eq_u32_e64 s[52:53], v73, v71
	v_or_b32_e32 v28, 3, v73
	v_writelane_b32 v250, s7, 60
	s_add_u32 s6, s66, 0x800
	v_cndmask_b32_e64 v123, 0, 1.0, vcc
	v_cmp_eq_u32_e32 vcc, v57, v71
	v_cndmask_b32_e64 v126, 0, 1.0, s[52:53]
	v_or_b32_e32 v57, 2, v73
	v_cmp_eq_u32_e64 s[52:53], v28, v70
	s_addc_u32 s7, s67, 0
	v_mad_u32_u24 v26, v111, s73, 0
	v_lshlrev_b32_e32 v27, 4, v27
	v_mul_lo_u32 v186, v168, s73
	v_mul_lo_u32 v52, v52, s73
	v_cndmask_b32_e64 v127, 0, 1.0, vcc
	v_cmp_eq_u32_e32 vcc, v57, v70
	v_cndmask_b32_e64 v129, 0, 1.0, s[52:53]
	v_cmp_eq_u32_e64 s[52:53], v28, v71
	v_writelane_b32 v250, s6, 61
	v_lshlrev_b32_e32 v28, 5, v0
	v_add_u32_e32 v50, 0xa00, v183
	v_add_u32_e32 v56, 0x1400, v183
	v_add_u32_e32 v55, 0, v186
	v_add_u32_e32 v190, s93, v110
	v_add_u32_e32 v64, s40, v185
	v_add_u32_e32 v65, s40, v186
	v_add_u32_e32 v67, s40, v52
	v_lshlrev_b32_e32 v52, 6, v70
	v_lshlrev_b32_e32 v54, 6, v71
	v_add_u32_e32 v116, s0, v169
	v_cndmask_b32_e64 v128, 0, 1.0, vcc
	v_cmp_eq_u32_e32 vcc, v57, v71
	v_writelane_b32 v250, s7, 62
	s_add_u32 s6, s68, 0x1000
	v_and_b32_e32 v28, 0x3800, v28
	v_add_u32_e32 v206, v26, v27
	v_add_u32_e32 v207, v181, v46
	v_mbcnt_lo_u32_b32 v26, -1, 0
	v_mov_b32_e32 v46, 0
	v_add_u32_e32 v194, s41, v110
	v_add_u32_e32 v195, s40, v110
	v_mul_u32_u24_e32 v196, 0xa0, v70
	v_mul_u32_u24_e32 v197, 0x90, v70
	v_lshl_add_u32 v198, v70, 2, s24
	v_ashrrev_i32_e32 v115, 31, v114
	v_mul_u32_u24_e32 v199, 0xa0, v71
	v_mul_u32_u24_e32 v200, 0x90, v71
	v_lshl_add_u32 v201, v71, 2, s24
	v_ashrrev_i32_e32 v117, 31, v116
	v_lshl_add_u32 v204, v73, 2, s24
	v_ashrrev_i32_e32 v121, 31, v120
	v_ashrrev_i32_e32 v125, 31, v124
	v_cndmask_b32_e64 v131, 0, 1.0, s[52:53]
	v_cndmask_b32_e64 v130, 0, 1.0, vcc
	s_addc_u32 s7, s69, 0
	v_lshl_add_u64 v[132:133], s[70:71], 0, v[28:29]
	s_mov_b32 s34, -1
	s_movk_i32 s71, 0x630
	s_mov_b32 s44, 0x3e0f83e1
	s_movk_i32 s45, 0xfdf0
	s_movk_i32 s46, 0x2940
	s_mov_b32 s47, 0x5040100
	s_mov_b32 s70, 0xbf60033a
	v_mbcnt_hi_u32_b32 v208, -1, v26
	s_add_i32 s48, 0, 0x12280
	s_movk_i32 s49, 0x2600
	v_add_u32_e32 v209, v50, v172
	v_add_u32_e32 v210, v51, v110
	v_add_u32_e32 v211, v53, v110
	v_add_u32_e32 v212, v189, v49
	v_add_u32_e32 v213, v60, v172
	v_add_u32_e32 v214, v62, v61
	v_add_u32_e32 v216, v64, v172
	v_add_u32_e32 v217, v65, v110
	v_lshlrev_b32_e32 v134, 1, v52
	v_add_u32_e32 v218, v68, v110
	v_add_u32_e32 v219, v69, v110
	v_lshlrev_b32_e32 v136, 1, v54
	v_add_u32_e32 v221, v47, v110
	v_add_u32_e32 v222, v48, v110
	v_add_u32_e32 v223, v56, v172
	v_mov_b32_e32 v139, v46
	v_add_u32_e32 v224, v55, v110
	v_add_u32_e32 v225, v190, v58
	v_add_u32_e32 v226, v190, v59
	v_add_u32_e32 v227, v66, v110
	v_add_u32_e32 v228, v67, v110
	s_mov_b32 s51, 0
	v_lshrrev_b32_e32 v26, 3, v0
	v_and_b32_e32 v27, 7, v0
	v_mul_u32_u24_e32 v26, 0x2600, v26
	v_lshl_add_u32 v251, v27, 4, v26
	v_mov_b32_e32 v26, v0
	v_lshrrev_b32_e32 v27, 4, v26
	v_mul_u32_u24_e32 v27, 0x7c2, v27
	v_lshrrev_b32_e32 v27, 16, v27
	v_mul_u32_u24_e32 v28, 0x210, v27
	v_sub_u32_e32 v26, v26, v28
	v_lshrrev_b32_e32 v28, 3, v26
	v_and_b32_e32 v26, 7, v26
	v_mul_u32_u24_e32 v28, 0x2600, v28
	v_lshl_add_u32 v28, v27, 10, v28
	v_lshl_add_u32 v252, v26, 4, v28
	v_add_u32_e32 v26, 0x200, v0
	v_lshrrev_b32_e32 v27, 4, v26
	v_mul_u32_u24_e32 v27, 0x7c2, v27
	v_lshrrev_b32_e32 v27, 16, v27
	v_mul_u32_u24_e32 v28, 0x210, v27
	v_sub_u32_e32 v26, v26, v28
	v_lshrrev_b32_e32 v28, 3, v26
	v_and_b32_e32 v26, 7, v26
	v_mul_u32_u24_e32 v28, 0x2600, v28
	v_lshl_add_u32 v28, v27, 10, v28
	v_lshl_add_u32 v253, v26, 4, v28
	v_add_u32_e32 v26, 0x400, v0
	v_lshrrev_b32_e32 v27, 4, v26
	v_mul_u32_u24_e32 v27, 0x7c2, v27
	v_lshrrev_b32_e32 v27, 16, v27
	v_mul_u32_u24_e32 v28, 0x210, v27
	v_sub_u32_e32 v26, v26, v28
	v_lshrrev_b32_e32 v28, 3, v26
	v_and_b32_e32 v26, 7, v26
	v_mul_u32_u24_e32 v28, 0x2600, v28
	v_lshl_add_u32 v28, v27, 10, v28
	v_lshl_add_u32 v254, v26, 4, v28
	v_add_u32_e32 v26, 0x600, v0
	v_lshrrev_b32_e32 v27, 4, v26
	v_mul_u32_u24_e32 v27, 0x7c2, v27
	v_lshrrev_b32_e32 v27, 16, v27
	v_mul_u32_u24_e32 v28, 0x210, v27
	v_sub_u32_e32 v26, v26, v28
	v_lshrrev_b32_e32 v28, 3, v26
	v_and_b32_e32 v26, 7, v26
	v_mul_u32_u24_e32 v28, 0x2600, v28
	v_lshl_add_u32 v28, v27, 10, v28
	v_lshl_add_u32 v255, v26, 4, v28
	s_branch .LBB0_295
.LBB0_294:
	v_mov_b32_e32 v137, v29
	s_nop 5
	v_cvt_pk_bf16_f32 v48, v78, v79
	v_cvt_pk_bf16_f32 v49, v80, v81
	v_lshl_add_u64 v[26:27], v[26:27], 0, v[136:137]
	global_store_dwordx2 v[26:27], v[48:49], off nt
	v_add_u32_e32 v26, v194, v200
	ds_read_b128 v[78:81], v26
	s_cmp_lg_u32 s51, s72
	s_waitcnt lgkmcnt(0)
	v_mfma_f32_16x16x32_bf16 v[74:77], v[74:77], v[78:81], 0
	ds_read_b128 v[78:81], v26 offset:64
	ds_read_b32 v26, v201
	s_waitcnt lgkmcnt(1)
	v_mfma_f32_16x16x32_bf16 v[70:73], v[70:73], v[78:81], v[74:77]
	s_nop 7
	v_pk_add_f32 v[48:49], v[126:127], v[70:71]
	v_pk_add_f32 v[70:71], v[130:131], v[72:73]
	s_waitcnt lgkmcnt(0)
	v_pk_mul_f32 v[48:49], v[26:27], v[48:49] op_sel_hi:[0,1]
	v_pk_mul_f32 v[26:27], v[26:27], v[70:71] op_sel_hi:[0,1]
	v_cvt_pk_bf16_f32 v48, v48, v49
	v_cvt_pk_bf16_f32 v49, v26, v27
	v_lshl_add_u64 v[26:27], v[124:125], 1, s[26:27]
	global_store_dwordx2 v[26:27], v[48:49], off nt
	v_add_u32_e32 v26, v190, v200
	ds_read_b128 v[70:73], v26
	v_add_u32_e32 v27, v195, v199
	ds_read_b128 v[74:77], v27 offset:10240
	s_waitcnt lgkmcnt(1)
	v_mfma_f32_16x16x32_bf16 v[70:73], v[94:97], v[70:73], 0
	s_waitcnt lgkmcnt(0)
	v_mfma_f32_16x16x32_bf16 v[70:73], v[98:101], v[74:77], v[70:73]
	ds_read_b128 v[74:77], v26 offset:64
	s_waitcnt lgkmcnt(0)
	v_mfma_f32_16x16x32_bf16 v[70:73], v[90:93], v[74:77], v[70:73]
	ds_read_b128 v[74:77], v27 offset:10304
	s_waitcnt lgkmcnt(0)
	v_mfma_f32_16x16x32_bf16 v[70:73], v[86:89], v[74:77], v[70:73]
	s_nop 7
	v_pk_mul_f32 v[26:27], v[68:69], v[72:73]
	v_pk_mul_f32 v[48:49], v[66:67], v[70:71]
	s_nop 0
	v_cvt_pk_bf16_f32 v48, v48, v49
	v_cvt_pk_bf16_f32 v49, v26, v27
	v_lshl_add_u64 v[26:27], v[116:117], 1, s[24:25]
	global_store_dwordx2 v[26:27], v[48:49], off nt
	s_waitcnt lgkmcnt(0)
	s_barrier
	s_cbranch_scc0 .LBB0_403

.LBB0_340:
	s_or_b64 exec, exec, s[24:25]
	s_and_b32 s35, s0, 1
	v_lshl_add_u32 v47, s35, 9, v180
	ds_read_b128 v[66:69], v47
	ds_read_b128 v[70:73], v47 offset:16
	ds_read_b128 v[74:77], v47 offset:256
	ds_read_b128 v[78:81], v47 offset:272
	s_waitcnt vmcnt(9)
	v_lshlrev_b32_e32 v26, 16, v2
	v_lshlrev_b32_e32 v49, 16, v6
	v_lshlrev_b32_e32 v48, 16, v10
	v_pk_add_f32 v[48:49], v[48:49], v[26:27] op_sel_hi:[1,0] neg_lo:[0,1] neg_hi:[0,1]
	s_waitcnt lgkmcnt(3)
	v_mov_b32_e32 v82, v66
	s_waitcnt lgkmcnt(1)
	v_mov_b32_e32 v83, v74
	v_pk_mul_f32 v[48:49], v[48:49], v[82:83]
	v_mov_b32_e32 v74, v67
	v_add_f32_e32 v26, v48, v26
	v_add_f32_e32 v26, v26, v49
	v_add_f32_e32 v26, v26, v26
	v_mul_f32_e32 v26, 0x3fb8aa3b, v26
	v_exp_f32_e32 v27, v26
	v_and_b32_e32 v26, 0xffff0000, v2
	v_and_b32_e32 v49, 0xffff0000, v6
	v_and_b32_e32 v48, 0xffff0000, v10
	v_pk_add_f32 v[48:49], v[48:49], v[26:27] op_sel_hi:[1,0] neg_lo:[0,1] neg_hi:[0,1]
	v_mov_b32_e32 v66, v68
	v_pk_mul_f32 v[48:49], v[48:49], v[74:75]
	v_mov_b32_e32 v67, v76
	v_add_f32_e32 v26, v48, v26
	v_add_f32_e32 v26, v26, v49
	v_add_f32_e32 v26, v26, v26
	v_mul_f32_e32 v26, 0x3fb8aa3b, v26
	v_exp_f32_e32 v28, v26
	v_add_f32_e32 v26, 1.0, v27
	v_lshlrev_b32_e32 v49, 16, v7
	v_lshlrev_b32_e32 v48, 16, v11
	v_add_f32_e32 v27, 1.0, v28
	v_lshlrev_b32_e32 v28, 16, v3
	v_pk_add_f32 v[48:49], v[48:49], v[28:29] op_sel_hi:[1,0] neg_lo:[0,1] neg_hi:[0,1]
	v_mov_b32_e32 v76, v69
	v_pk_mul_f32 v[48:49], v[48:49], v[66:67]
	v_lshlrev_b32_e32 v67, 16, v8
	v_add_f32_e32 v28, v48, v28
	v_add_f32_e32 v28, v28, v49
	v_add_f32_e32 v28, v28, v28
	v_mul_f32_e32 v28, 0x3fb8aa3b, v28
	v_exp_f32_e32 v66, v28
	v_and_b32_e32 v28, 0xffff0000, v3
	v_and_b32_e32 v49, 0xffff0000, v7
	v_and_b32_e32 v48, 0xffff0000, v11
	v_pk_add_f32 v[48:49], v[48:49], v[28:29] op_sel_hi:[1,0] neg_lo:[0,1] neg_hi:[0,1]
	v_mov_b32_e32 v68, v70
	v_pk_mul_f32 v[48:49], v[48:49], v[76:77]
	s_waitcnt lgkmcnt(0)
	v_mov_b32_e32 v69, v78
	v_add_f32_e32 v28, v48, v28
	v_add_f32_e32 v28, v28, v49
	v_add_f32_e32 v28, v28, v28
	v_mul_f32_e32 v28, 0x3fb8aa3b, v28
	v_exp_f32_e32 v28, v28
	v_add_f32_e32 v48, 1.0, v66
	v_lshlrev_b32_e32 v66, 16, v12
	v_mov_b32_e32 v78, v71
	v_add_f32_e32 v49, 1.0, v28
	v_lshlrev_b32_e32 v28, 16, v4
	v_pk_add_f32 v[66:67], v[66:67], v[28:29] op_sel_hi:[1,0] neg_lo:[0,1] neg_hi:[0,1]
	v_mov_b32_e32 v70, v72
	v_pk_mul_f32 v[66:67], v[66:67], v[68:69]
	v_lshlrev_b32_e32 v69, 16, v9
	v_add_f32_e32 v28, v66, v28
	v_add_f32_e32 v28, v28, v67
	v_add_f32_e32 v28, v28, v28
	v_mul_f32_e32 v28, 0x3fb8aa3b, v28
	v_exp_f32_e32 v68, v28
	v_and_b32_e32 v28, 0xffff0000, v4
	v_and_b32_e32 v67, 0xffff0000, v8
	v_and_b32_e32 v66, 0xffff0000, v12
	v_pk_add_f32 v[66:67], v[66:67], v[28:29] op_sel_hi:[1,0] neg_lo:[0,1] neg_hi:[0,1]
	v_mov_b32_e32 v71, v80
	v_pk_mul_f32 v[66:67], v[66:67], v[78:79]
	v_mov_b32_e32 v80, v73
	v_add_f32_e32 v28, v66, v28
	v_add_f32_e32 v28, v28, v67
	v_add_f32_e32 v28, v28, v28
	v_mul_f32_e32 v28, 0x3fb8aa3b, v28
	v_exp_f32_e32 v28, v28
	v_add_f32_e32 v66, 1.0, v68
	v_lshlrev_b32_e32 v68, 16, v13
	v_rcp_f32_e32 v26, v26
	v_add_f32_e32 v67, 1.0, v28
	v_lshlrev_b32_e32 v28, 16, v5
	v_pk_add_f32 v[68:69], v[68:69], v[28:29] op_sel_hi:[1,0] neg_lo:[0,1] neg_hi:[0,1]
	v_rcp_f32_e32 v27, v27
	v_pk_mul_f32 v[68:69], v[68:69], v[70:71]
	v_rcp_f32_e32 v48, v48
	v_add_f32_e32 v28, v68, v28
	v_add_f32_e32 v28, v28, v69
	v_add_f32_e32 v28, v28, v28
	v_mul_f32_e32 v28, 0x3fb8aa3b, v28
	v_exp_f32_e32 v70, v28
	v_and_b32_e32 v28, 0xffff0000, v5
	v_and_b32_e32 v69, 0xffff0000, v9
	v_and_b32_e32 v68, 0xffff0000, v13
	v_pk_add_f32 v[68:69], v[68:69], v[28:29] op_sel_hi:[1,0] neg_lo:[0,1] neg_hi:[0,1]
	v_rcp_f32_e32 v49, v49
	v_pk_mul_f32 v[68:69], v[68:69], v[80:81]
	v_rcp_f32_e32 v66, v66
	v_add_f32_e32 v28, v68, v28
	v_add_f32_e32 v28, v28, v69
	v_add_f32_e32 v28, v28, v28
	v_mul_f32_e32 v28, 0x3fb8aa3b, v28
	v_exp_f32_e32 v28, v28
	v_add_f32_e32 v68, 1.0, v70
	v_rcp_f32_e32 v67, v67
	v_rcp_f32_e32 v68, v68
	v_add_f32_e32 v28, 1.0, v28
	v_rcp_f32_e32 v69, v28
	v_pk_fma_f32 v[26:27], v[26:27], 2.0, 1.0 op_sel_hi:[1,0,0] neg_lo:[1,0,0] neg_hi:[1,0,0]
	v_pk_fma_f32 v[48:49], v[48:49], 2.0, 1.0 op_sel_hi:[1,0,0] neg_lo:[1,0,0] neg_hi:[1,0,0]
	v_pk_fma_f32 v[70:71], v[66:67], 2.0, 1.0 op_sel_hi:[1,0,0] neg_lo:[1,0,0] neg_hi:[1,0,0]
	v_pk_fma_f32 v[72:73], v[68:69], 2.0, 1.0 op_sel_hi:[1,0,0] neg_lo:[1,0,0] neg_hi:[1,0,0]
	v_cvt_pk_bf16_f32 v66, v26, v27
	v_cvt_pk_bf16_f32 v67, v48, v49
	v_cvt_pk_bf16_f32 v68, v70, v71
	v_cvt_pk_bf16_f32 v69, v72, v73
	ds_write_b128 v206, v[66:69] offset:32768
	ds_read_b128 v[66:69], v47 offset:1024
	ds_read_b128 v[70:73], v47 offset:1040
	ds_read_b128 v[74:77], v47 offset:1280
	ds_read_b128 v[78:81], v47 offset:1296
	s_waitcnt vmcnt(8)
	v_lshlrev_b32_e32 v26, 16, v14
	v_and_b32_e32 v27, 0xffff0000, v14
	v_lshlrev_b32_e32 v48, 16, v22
	v_and_b32_e32 v49, 0xffff0000, v22
	v_lshlrev_b32_e32 v82, 16, v18
	v_and_b32_e32 v83, 0xffff0000, v18
	v_pk_add_f32 v[48:49], v[48:49], v[26:27] neg_lo:[0,1] neg_hi:[0,1]
	s_bitcmp1_b32 s0, 0
	s_waitcnt lgkmcnt(3)
	v_pk_fma_f32 v[48:49], v[48:49], v[66:67], v[26:27]
	v_pk_add_f32 v[26:27], v[82:83], v[26:27] neg_lo:[0,1] neg_hi:[0,1]
	v_lshlrev_b32_e32 v66, 16, v23
	s_waitcnt lgkmcnt(1)
	v_pk_fma_f32 v[26:27], v[26:27], v[74:75], v[48:49]
	v_lshlrev_b32_e32 v48, 16, v15
	v_and_b32_e32 v49, 0xffff0000, v15
	v_and_b32_e32 v67, 0xffff0000, v23
	v_lshlrev_b32_e32 v74, 16, v19
	v_and_b32_e32 v75, 0xffff0000, v19
	v_pk_add_f32 v[66:67], v[66:67], v[48:49] neg_lo:[0,1] neg_hi:[0,1]
	s_cselect_b64 s[54:55], -1, 0
	v_pk_fma_f32 v[66:67], v[66:67], v[68:69], v[48:49]
	v_pk_add_f32 v[48:49], v[74:75], v[48:49] neg_lo:[0,1] neg_hi:[0,1]
	v_lshlrev_b32_e32 v68, 16, v24
	v_pk_fma_f32 v[48:49], v[48:49], v[76:77], v[66:67]
	v_lshlrev_b32_e32 v66, 16, v16
	v_and_b32_e32 v67, 0xffff0000, v16
	v_and_b32_e32 v69, 0xffff0000, v24
	v_lshlrev_b32_e32 v74, 16, v20
	v_and_b32_e32 v75, 0xffff0000, v20
	v_pk_add_f32 v[68:69], v[68:69], v[66:67] neg_lo:[0,1] neg_hi:[0,1]
	s_waitcnt vmcnt(8)
	v_lshrrev_b32_e32 v28, 16, v58
	v_pk_fma_f32 v[68:69], v[68:69], v[70:71], v[66:67]
	v_pk_add_f32 v[66:67], v[74:75], v[66:67] neg_lo:[0,1] neg_hi:[0,1]
	v_lshlrev_b32_e32 v70, 16, v25
	s_waitcnt lgkmcnt(0)
	v_pk_fma_f32 v[68:69], v[66:67], v[78:79], v[68:69]
	v_lshlrev_b32_e32 v66, 16, v17
	v_and_b32_e32 v67, 0xffff0000, v17
	v_and_b32_e32 v71, 0xffff0000, v25
	v_lshlrev_b32_e32 v74, 16, v21
	v_and_b32_e32 v75, 0xffff0000, v21
	v_pk_add_f32 v[70:71], v[70:71], v[66:67] neg_lo:[0,1] neg_hi:[0,1]
	v_cvt_pk_bf16_f32 v68, v68, v69
	v_pk_fma_f32 v[70:71], v[70:71], v[72:73], v[66:67]
	v_pk_add_f32 v[66:67], v[74:75], v[66:67] neg_lo:[0,1] neg_hi:[0,1]
	v_lshrrev_b32_e32 v47, 16, v50
	v_pk_fma_f32 v[70:71], v[66:67], v[80:81], v[70:71]
	v_cvt_pk_bf16_f32 v66, v26, v27
	v_cvt_pk_bf16_f32 v67, v48, v49
	v_cvt_pk_bf16_f32 v69, v70, v71
	ds_write_b128 v206, v[66:69] offset:43008
	v_cndmask_b32_e64 v28, v47, v28, s[54:55]
	s_waitcnt vmcnt(8)
	v_lshrrev_b32_e32 v47, 16, v62
	v_lshrrev_b32_e32 v48, 16, v54
	v_lshrrev_b32_e32 v49, 16, v59
	v_lshrrev_b32_e32 v66, 16, v51
	s_waitcnt lgkmcnt(0)
	s_barrier
	v_cndmask_b32_e64 v47, v48, v47, s[54:55]
	v_cndmask_b32_e64 v48, v51, v59, s[54:55]
	v_cndmask_b32_e64 v49, v66, v49, s[54:55]
	v_add_u32_e32 v86, v181, v167
	v_perm_b32 v67, v49, v48, s47
	v_lshrrev_b32_e32 v49, 16, v63
	v_lshrrev_b32_e32 v66, 16, v55
	ds_read_b128 v[74:77], v86
	ds_read_b128 v[78:81], v86 offset:64
	v_cndmask_b32_e64 v48, v55, v63, s[54:55]
	v_cndmask_b32_e64 v49, v66, v49, s[54:55]
	v_perm_b32 v71, v49, v48, s47
	v_lshrrev_b32_e32 v49, 16, v60
	v_lshrrev_b32_e32 v66, 16, v52
	v_cndmask_b32_e64 v48, v52, v60, s[54:55]
	v_cndmask_b32_e64 v49, v66, v49, s[54:55]
	v_perm_b32 v68, v49, v48, s47
	v_lshrrev_b32_e32 v49, 16, v64
	v_lshrrev_b32_e32 v66, 16, v56
	v_cndmask_b32_e64 v48, v56, v64, s[54:55]
	v_cndmask_b32_e64 v49, v66, v49, s[54:55]
	v_perm_b32 v72, v49, v48, s47
	v_lshrrev_b32_e32 v49, 16, v61
	v_lshrrev_b32_e32 v66, 16, v53
	v_cndmask_b32_e64 v26, v50, v58, s[54:55]
	v_cndmask_b32_e64 v48, v53, v61, s[54:55]
	v_cndmask_b32_e64 v49, v66, v49, s[54:55]
	v_perm_b32 v69, v49, v48, s47
	v_perm_b32 v66, v28, v26, s47
	v_lshrrev_b32_e32 v49, 16, v65
	v_lshrrev_b32_e32 v70, 16, v57
	s_waitcnt lgkmcnt(1)
	v_mfma_f32_16x16x32_bf16 v[74:77], v[74:77], v[66:69], 0
	v_cndmask_b32_e64 v27, v54, v62, s[54:55]
	v_cndmask_b32_e64 v48, v57, v65, s[54:55]
	v_cndmask_b32_e64 v26, v70, v49, s[54:55]
	v_perm_b32 v73, v26, v48, s47
	v_perm_b32 v70, v47, v27, s47
	ds_read_b128 v[82:85], v86 offset:2624
	v_mov_b32_e32 v26, v0
	s_waitcnt lgkmcnt(1)
	v_mfma_f32_16x16x32_bf16 v[74:77], v[78:81], v[70:73], v[74:77]
	ds_read_b128 v[78:81], v86 offset:2560
	s_bfe_i32 s24, s0, 0x10000
	s_lshl_b32 s26, s35, 8
	s_waitcnt lgkmcnt(0)
	v_mfma_f32_16x16x32_bf16 v[78:81], v[78:81], v[66:69], 0
	v_mfma_f32_16x16x32_bf16 v[78:81], v[82:85], v[70:73], v[78:81]
	ds_read_b128 v[82:85], v86 offset:5120
	ds_read_b128 v[86:89], v86 offset:5184
	s_waitcnt lgkmcnt(1)
	v_mfma_f32_16x16x32_bf16 v[82:85], v[82:85], v[66:69], 0
	s_waitcnt lgkmcnt(0)
	v_mfma_f32_16x16x32_bf16 v[82:85], v[86:89], v[70:73], v[82:85]
	ds_read_b128 v[86:89], v207
	s_waitcnt lgkmcnt(0)
	v_mfma_f32_16x16x32_bf16 v[66:69], v[86:89], v[66:69], 0
	ds_read_b128 v[86:89], v207 offset:64
	s_waitcnt lgkmcnt(0)
	v_mfma_f32_16x16x32_bf16 v[66:69], v[86:89], v[70:73], v[66:69]
	ds_write2st64_b32 v182, v74, v75 offset1:1
	ds_write2st64_b32 v182, v76, v77 offset0:2 offset1:3
	ds_write2st64_b32 v182, v78, v79 offset0:16 offset1:17
	ds_write2st64_b32 v182, v80, v81 offset0:18 offset1:19
	ds_write2st64_b32 v182, v82, v83 offset0:32 offset1:33
	ds_write2st64_b32 v182, v84, v85 offset0:34 offset1:35
	s_nop 1
	ds_write2st64_b32 v182, v66, v67 offset0:48 offset1:49
	ds_write2st64_b32 v182, v68, v69 offset0:50 offset1:51
	s_waitcnt lgkmcnt(0)
	s_barrier
	s_nop 0
	v_and_b32_e32 v47, 31, v26
	v_bfe_u32 v28, v26, 5, 1
	v_mov_b32_e32 v26, s92
	v_bitop3_b32 v26, v28, s24, v26 bitop3:0x36
	v_or_b32_e32 v135, s92, v28
	v_lshlrev_b32_e32 v66, 1, v47
	v_lshlrev_b32_e32 v26, 4, v26
	v_bitop3_b32 v26, v26, v66, 48 bitop3:0x6c
	v_lshlrev_b32_e32 v67, 2, v135
	s_add_i32 s24, s26, 0
	v_lshl_add_u32 v74, v26, 2, 0
	v_sub_u32_e32 v26, 63, v67
	v_lshl_add_u32 v27, v47, 3, s24
	v_cndmask_b32_e64 v146, v67, v26, s[54:55]
	v_or_b32_e32 v234, 1, v67
	v_add_u32_e32 v27, 0x24800, v27
	v_lshlrev_b32_e32 v26, 8, v146
	v_sub_u32_e32 v68, 63, v234
	v_add_u32_e32 v147, v74, v26
	ds_read_b64 v[26:27], v27
	ds_read_b64 v[48:49], v147
	v_cndmask_b32_e64 v98, v234, v68, s[54:55]
	v_lshlrev_b32_e32 v68, 8, v98
	v_add_u32_e32 v99, v74, v68
	v_or_b32_e32 v68, 2, v67
	ds_read_b64 v[70:71], v99
	v_sub_u32_e32 v69, 63, v68
	v_cndmask_b32_e64 v94, v68, v69, s[54:55]
	s_waitcnt lgkmcnt(1)
	v_pk_add_f32 v[48:49], v[26:27], v[48:49]
	v_lshlrev_b32_e32 v69, 8, v94
	v_mul_f32_e32 v48, 0xbfb8aa3b, v48
	v_add_u32_e32 v95, v74, v69
	v_exp_f32_e32 v69, v48
	v_mul_f32_e32 v48, 0xbfb8aa3b, v49
	v_exp_f32_e32 v73, v48
	ds_read_b64 v[48:49], v95
	s_waitcnt lgkmcnt(1)
	v_pk_add_f32 v[70:71], v[26:27], v[70:71]
	v_add_f32_e32 v69, 1.0, v69
	v_mul_f32_e32 v70, 0xbfb8aa3b, v70
	v_exp_f32_e32 v70, v70
	v_rcp_f32_e32 v72, v69
	v_add_f32_e32 v69, 1.0, v73
	s_waitcnt lgkmcnt(0)
	v_pk_add_f32 v[48:49], v[26:27], v[48:49]
	v_rcp_f32_e32 v73, v69
	v_add_f32_e32 v69, 1.0, v70
	v_mul_f32_e32 v48, 0xbfb8aa3b, v48
	v_rcp_f32_e32 v70, v69
	v_exp_f32_e32 v76, v48
	v_mul_f32_e32 v48, 0xbfb8aa3b, v49
	v_or_b32_e32 v69, 3, v67
	v_exp_f32_e32 v77, v48
	v_sub_u32_e32 v48, 63, v69
	v_cndmask_b32_e64 v48, v69, v48, s[54:55]
	v_lshlrev_b32_e32 v49, 8, v48
	v_add_u32_e32 v49, v74, v49
	ds_read_b64 v[74:75], v49
	v_mul_f32_e32 v71, 0xbfb8aa3b, v71
	v_exp_f32_e32 v71, v71
	v_add_f32_e32 v76, 1.0, v76
	v_add_f32_e32 v77, 1.0, v77
	s_waitcnt lgkmcnt(0)
	v_pk_add_f32 v[26:27], v[26:27], v[74:75]
	v_add_f32_e32 v71, 1.0, v71
	v_mul_f32_e32 v26, 0xbfb8aa3b, v26
	v_mul_f32_e32 v27, 0xbfb8aa3b, v27
	v_exp_f32_e32 v26, v26
	v_exp_f32_e32 v27, v27
	v_rcp_f32_e32 v71, v71
	v_rcp_f32_e32 v76, v76
	v_rcp_f32_e32 v77, v77
	v_add_f32_e32 v26, 1.0, v26
	v_add_f32_e32 v27, 1.0, v27
	v_pk_fma_f32 v[148:149], v[72:73], s[70:71], 0 op_sel_hi:[1,0,0]
	v_rcp_f32_e32 v26, v26
	v_rcp_f32_e32 v27, v27
	v_pk_fma_f32 v[100:101], v[70:71], s[70:71], v[148:149] op_sel_hi:[1,0,1]
	v_and_b32_e32 v71, 64, v208
	v_xor_b32_e32 v70, 32, v208
	v_add_u32_e32 v71, 64, v71
	v_cmp_lt_i32_e32 vcc, v70, v71
	v_pk_fma_f32 v[96:97], v[76:77], s[70:71], v[100:101] op_sel_hi:[1,0,1]
	v_cmp_eq_u32_e64 s[52:53], 0, v28
	v_cndmask_b32_e32 v70, v208, v70, vcc
	v_pk_fma_f32 v[26:27], v[26:27], s[70:71], v[96:97] op_sel_hi:[1,0,1]
	v_lshlrev_b32_e32 v70, 2, v70
	ds_bpermute_b32 v152, v70, v26
	ds_bpermute_b32 v153, v70, v27
	s_and_saveexec_b64 s[24:25], s[52:53]
	s_cbranch_execz .LBB0_342
	v_readlane_b32 s27, v250, 25
	s_waitcnt lgkmcnt(0)
	v_pk_add_f32 v[70:71], v[26:27], v[152:153]
	v_lshl_add_u32 v28, v66, 2, s27
	ds_write_b64 v28, v[70:71] offset:32768

.LBB0_397:
	s_lshl_b32 s0, s35, 5
	s_lshl_b32 s24, s24, 3
	s_add_i32 s24, s24, s0
	v_add_u32_e32 v27, v203, v196
	s_or_b32 s26, s24, s50
	ds_read_b64 v[48:49], v27 offset:63488
	s_ashr_i32 s27, s26, 31
	s_lshl_b32 s0, s25, 12
	s_lshl_b64 s[26:27], s[26:27], 18
	s_xor_b32 s28, s0, 0x3f000
	s_and_b64 s[24:25], s[54:55], exec
	s_cselect_b32 s0, s28, s0
	s_or_b32 s26, s26, s0
	s_waitcnt lgkmcnt(0)
	v_lshlrev_b32_e32 v94, 16, v48
	v_and_b32_e32 v95, 0xffff0000, v48
	s_lshl_b64 s[28:29], s[26:27], 1
	v_pk_add_f32 v[90:91], v[90:91], v[94:95]
	s_add_u32 s54, s58, s28
	v_cvt_pk_bf16_f32 v48, v90, v91
	v_lshlrev_b32_e32 v90, 16, v49
	v_and_b32_e32 v91, 0xffff0000, v49
	s_addc_u32 s55, s59, s29
	v_pk_add_f32 v[90:91], v[92:93], v[90:91]
	v_add_u32_e32 v27, v193, v196
	v_cvt_pk_bf16_f32 v49, v90, v91
	v_lshl_add_u64 v[90:91], v[120:121], 1, s[54:55]
	global_store_dwordx2 v[90:91], v[48:49], off nt
	ds_read_b128 v[90:93], v27
	s_waitcnt lgkmcnt(0)
	v_mfma_f32_16x16x32_bf16 v[90:93], v[78:81], v[90:93], 0
	s_and_b64 vcc, exec, s[56:57]
	v_mfma_f32_16x16x32_bf16 v[86:89], v[82:85], v[86:89], v[90:93]
	s_cbranch_vccnz .LBB0_399
	s_nop 4
	ds_read_b128 v[90:93], v227 offset:64
	ds_read_b128 v[94:97], v27 offset:64
	s_waitcnt lgkmcnt(0)
	v_mfma_f32_16x16x32_bf16 v[86:89], v[90:93], v[94:97], v[86:89]
	ds_read_b128 v[90:93], v228 offset:64
	ds_read_b128 v[94:97], v26 offset:64
	s_waitcnt lgkmcnt(0)
	v_mfma_f32_16x16x32_bf16 v[86:89], v[90:93], v[94:97], v[86:89]
.LBB0_399:
	v_lshl_add_u64 v[26:27], v[118:119], 0, s[28:29]
	v_mov_b32_e32 v135, v29
	s_nop 5
	v_cvt_pk_bf16_f32 v48, v86, v87
	v_cvt_pk_bf16_f32 v49, v88, v89
	v_lshl_add_u64 v[86:87], v[26:27], 0, v[134:135]
	v_add_u32_e32 v28, v194, v197
	global_store_dwordx2 v[86:87], v[48:49], off nt
	ds_read_b128 v[86:89], v28
	ds_read_b128 v[90:93], v28 offset:64
	s_waitcnt lgkmcnt(1)
	v_mfma_f32_16x16x32_bf16 v[86:89], v[74:77], v[86:89], 0
	ds_read_b32 v28, v198
	ds_read_b128 v[94:97], v218
	s_add_u32 s26, s96, s28
	s_waitcnt lgkmcnt(2)
	v_mfma_f32_16x16x32_bf16 v[86:89], v[70:73], v[90:93], v[86:89]
	s_addc_u32 s27, s97, s29
	ds_read_b128 v[98:101], v219
	v_add_u32_e32 v47, v195, v196
	ds_read_b128 v[90:93], v47 offset:10240
	s_add_u32 s24, s88, s28
	s_nop 2
	v_pk_add_f32 v[48:49], v[122:123], v[86:87]
	v_pk_add_f32 v[86:87], v[128:129], v[88:89]
	s_waitcnt lgkmcnt(3)
	v_pk_mul_f32 v[48:49], v[28:29], v[48:49] op_sel_hi:[0,1]
	v_pk_mul_f32 v[86:87], v[28:29], v[86:87] op_sel_hi:[0,1]
	v_cvt_pk_bf16_f32 v48, v48, v49
	v_cvt_pk_bf16_f32 v49, v86, v87
	v_lshl_add_u64 v[86:87], v[120:121], 1, s[26:27]
	v_add_u32_e32 v28, v190, v197
	global_store_dwordx2 v[86:87], v[48:49], off nt
	ds_read_b128 v[86:89], v28
	s_waitcnt lgkmcnt(0)
	v_mfma_f32_16x16x32_bf16 v[86:89], v[94:97], v[86:89], 0
	s_addc_u32 s25, s89, s29
	s_and_b64 vcc, exec, s[56:57]
	v_mfma_f32_16x16x32_bf16 v[86:89], v[98:101], v[90:93], v[86:89]
	ds_read_b128 v[90:93], v218 offset:64
	ds_read_b128 v[102:105], v28 offset:64
	v_add_u32_e32 v28, v192, v199
	s_waitcnt lgkmcnt(0)
	v_mfma_f32_16x16x32_bf16 v[102:105], v[90:93], v[102:105], v[86:89]
	s_nop 2
	ds_read_b128 v[86:89], v219 offset:64
	ds_read_b128 v[106:109], v47 offset:10304
	s_waitcnt lgkmcnt(0)
	v_mfma_f32_16x16x32_bf16 v[102:105], v[86:89], v[106:109], v[102:105]
	s_nop 7
	v_pk_mul_f32 v[48:49], v[68:69], v[104:105]
	v_pk_mul_f32 v[102:103], v[66:67], v[102:103]
	s_nop 0
	v_cvt_pk_bf16_f32 v102, v102, v103
	v_cvt_pk_bf16_f32 v103, v48, v49
	v_lshl_add_u64 v[48:49], v[114:115], 1, s[24:25]
	global_store_dwordx2 v[48:49], v[102:103], off nt
	ds_read_b128 v[102:105], v28
	s_waitcnt lgkmcnt(0)
	v_mfma_f32_16x16x32_bf16 v[106:109], v[74:77], v[102:105], 0
	s_cbranch_vccnz .LBB0_401
	ds_read_b128 v[140:143], v28 offset:64
	s_waitcnt lgkmcnt(0)
	v_mfma_f32_16x16x32_bf16 v[106:109], v[70:73], v[140:143], v[106:109]
.LBB0_401:
	v_add_u32_e32 v47, v203, v199
	ds_read_b64 v[48:49], v47 offset:63488
	v_add_u32_e32 v47, v193, v199
	s_and_b64 vcc, exec, s[56:57]
	s_waitcnt lgkmcnt(0)
	v_lshlrev_b32_e32 v140, 16, v48
	v_and_b32_e32 v141, 0xffff0000, v48
	s_nop 0
	v_pk_add_f32 v[106:107], v[106:107], v[140:141]
	s_nop 0
	v_cvt_pk_bf16_f32 v48, v106, v107
	v_lshlrev_b32_e32 v106, 16, v49
	v_and_b32_e32 v107, 0xffff0000, v49
	v_pk_add_f32 v[106:107], v[108:109], v[106:107]
	s_nop 0
	v_cvt_pk_bf16_f32 v49, v106, v107
	v_lshl_add_u64 v[106:107], v[124:125], 1, s[54:55]
	global_store_dwordx2 v[106:107], v[48:49], off nt
	ds_read_b128 v[106:109], v47
	s_waitcnt lgkmcnt(0)
	v_mfma_f32_16x16x32_bf16 v[78:81], v[78:81], v[106:109], 0
	v_mfma_f32_16x16x32_bf16 v[78:81], v[82:85], v[102:105], v[78:81]
	s_cbranch_vccnz .LBB0_294
	ds_read_b128 v[82:85], v227 offset:64
	ds_read_b128 v[102:105], v47 offset:64
	s_waitcnt lgkmcnt(0)
	v_mfma_f32_16x16x32_bf16 v[78:81], v[82:85], v[102:105], v[78:81]
	ds_read_b128 v[82:85], v228 offset:64
	ds_read_b128 v[102:105], v28 offset:64
	s_waitcnt lgkmcnt(0)
	v_mfma_f32_16x16x32_bf16 v[78:81], v[82:85], v[102:105], v[78:81]
	s_branch .LBB0_294

.LBB0_463:
	s_or_b64 exec, exec, s[2:3]
	v_readlane_b32 s0, v250, 18
	v_readlane_b32 s1, v250, 3
	v_readfirstlane_b32 s2, v0
	v_and_b32_e32 v1, 63, v0
	v_and_b32_e32 v12, 15, v1
	v_lshrrev_b32_e32 v13, 4, v1
	s_lshr_b32 s2, s2, 6
	s_and_b32 s3, s2, 1
	s_lshr_b32 s4, s2, 1
	s_and_b32 s1, s1, 1
	s_ashr_i32 s0, s0, 1
	s_lshl_b32 s0, s0, 19
	s_lshl_b32 s5, s4, 11
	v_lshl_add_u32 v14, v1, 4, s5
	v_mov_b32_e32 v15, 0
	s_lshl_b32 s5, s4, 4
	v_add_u32_e32 v16, s5, v12
	v_lshlrev_b32_e32 v16, 6, v16
	s_lshl_b32 s5, s1, 5
	v_lshl_add_u32 v17, v13, 2, s5
	v_add_u32_e32 v16, v16, v17
	v_lshlrev_b32_e32 v16, 1, v16
	v_mov_b32_e32 v17, 0
	s_lshl_b32 s5, s1, 3
	s_add_i32 s5, s5, s4
	s_lshl_b32 s5, s5, 9
	v_lshl_add_u32 v18, v1, 3, s5
	v_mov_b32_e32 v19, 0
	s_mov_b32 s8, 0x2000
	s_mov_b32 s9, 0
	v_mul_u32_u24_e32 v10, 0xa0, v12
	s_lshl_b32 s5, s4, 5
	v_lshl_add_u32 v11, v13, 3, s5
	v_add_u32_e32 v11, v11, v10
	v_lshl_add_u32 v10, v13, 4, v10
	s_cmp_eq_u32 s3, 0
	s_cbranch_scc0 .Lsp_hrole
	s_add_u32 s6, s58, s0
	s_addc_u32 s7, s59, 0
	v_lshl_add_u64 v[2:3], s[6:7], 0, v[14:15]
	s_add_u32 s6, s48, s0
	s_addc_u32 s7, s49, 0
	v_lshl_add_u64 v[6:7], s[6:7], 0, v[16:17]
	v_lshl_add_u64 v[182:183], s[6:7], 0, v[16:17]
	global_load_dwordx4 v[20:23], v[2:3], off
	global_load_dwordx4 v[24:27], v[2:3], off offset:1024
	global_load_dwordx2 v[28:29], v[6:7], off
	global_load_dwordx2 v[30:31], v[6:7], off offset:32
	v_lshl_add_u64 v[2:3], v[2:3], 0, s[8:9]
	v_lshl_add_u64 v[6:7], v[6:7], 0, s[8:9]
	global_load_dwordx4 v[32:35], v[2:3], off
	global_load_dwordx4 v[36:39], v[2:3], off offset:1024
	global_load_dwordx2 v[40:41], v[6:7], off
	global_load_dwordx2 v[42:43], v[6:7], off offset:32
	v_lshl_add_u64 v[2:3], v[2:3], 0, s[8:9]
	v_lshl_add_u64 v[6:7], v[6:7], 0, s[8:9]
	global_load_dwordx4 v[44:47], v[2:3], off
	global_load_dwordx4 v[48:51], v[2:3], off offset:1024
	global_load_dwordx2 v[52:53], v[6:7], off
	global_load_dwordx2 v[54:55], v[6:7], off offset:32
	v_lshl_add_u64 v[2:3], v[2:3], 0, s[8:9]
	v_lshl_add_u64 v[6:7], v[6:7], 0, s[8:9]
	global_load_dwordx4 v[56:59], v[2:3], off
	global_load_dwordx4 v[60:63], v[2:3], off offset:1024
	global_load_dwordx2 v[64:65], v[6:7], off
	global_load_dwordx2 v[66:67], v[6:7], off offset:32
	v_lshl_add_u64 v[2:3], v[2:3], 0, s[8:9]
	v_lshl_add_u64 v[6:7], v[6:7], 0, s[8:9]
	global_load_dwordx4 v[68:71], v[2:3], off
	global_load_dwordx4 v[72:75], v[2:3], off offset:1024
	global_load_dwordx2 v[76:77], v[6:7], off
	global_load_dwordx2 v[78:79], v[6:7], off offset:32
	v_lshl_add_u64 v[2:3], v[2:3], 0, s[8:9]
	v_lshl_add_u64 v[6:7], v[6:7], 0, s[8:9]
	global_load_dwordx4 v[80:83], v[2:3], off
	global_load_dwordx4 v[84:87], v[2:3], off offset:1024
	global_load_dwordx2 v[88:89], v[6:7], off
	global_load_dwordx2 v[90:91], v[6:7], off offset:32
	v_lshl_add_u64 v[2:3], v[2:3], 0, s[8:9]
	v_lshl_add_u64 v[6:7], v[6:7], 0, s[8:9]
	global_load_dwordx4 v[92:95], v[2:3], off
	global_load_dwordx4 v[96:99], v[2:3], off offset:1024
	global_load_dwordx2 v[100:101], v[6:7], off
	global_load_dwordx2 v[102:103], v[6:7], off offset:32
	v_lshl_add_u64 v[2:3], v[2:3], 0, s[8:9]
	v_lshl_add_u64 v[6:7], v[6:7], 0, s[8:9]
	s_waitcnt lgkmcnt(0)
	s_barrier
	global_load_dwordx4 v[104:107], v[2:3], off
	global_load_dwordx4 v[108:111], v[2:3], off offset:1024
	global_load_dwordx2 v[112:113], v[6:7], off
	global_load_dwordx2 v[114:115], v[6:7], off offset:32
	v_lshl_add_u64 v[2:3], v[2:3], 0, s[8:9]
	v_lshl_add_u64 v[6:7], v[6:7], 0, s[8:9]
	ds_read_b128 v[184:187], v10
	ds_read_b128 v[192:195], v10 offset:2560
	ds_read_b128 v[188:191], v10 offset:64
	ds_read_b128 v[196:199], v10 offset:2624
	s_waitcnt vmcnt(28)
	v_lshlrev_b32_e32 v200, 16, v28
	v_and_b32_e32 v201, 0xffff0000, v28
	v_lshlrev_b32_e32 v202, 16, v29
	v_and_b32_e32 v203, 0xffff0000, v29
	v_lshlrev_b32_e32 v204, 16, v30
	v_and_b32_e32 v205, 0xffff0000, v30
	v_lshlrev_b32_e32 v206, 16, v31
	v_and_b32_e32 v207, 0xffff0000, v31
	s_waitcnt lgkmcnt(2)
	v_mfma_f32_16x16x32_bf16 v[200:203], v[184:187], v[20:23], v[200:203]
	v_mfma_f32_16x16x32_bf16 v[204:207], v[192:195], v[20:23], v[204:207]
	s_waitcnt lgkmcnt(0)
	v_mfma_f32_16x16x32_bf16 v[200:203], v[188:191], v[24:27], v[200:203]
	v_mfma_f32_16x16x32_bf16 v[204:207], v[196:199], v[24:27], v[204:207]
	s_nop 6
	v_cvt_pk_bf16_f32 v200, v200, v201
	v_cvt_pk_bf16_f32 v201, v202, v203
	v_cvt_pk_bf16_f32 v204, v204, v205
	v_cvt_pk_bf16_f32 v205, v206, v207
	global_store_dwordx2 v[182:183], v[200:201], off
	global_store_dwordx2 v[182:183], v[204:205], off offset:32
	v_lshl_add_u64 v[182:183], v[182:183], 0, s[8:9]
	s_waitcnt lgkmcnt(0)
	s_barrier
	global_load_dwordx4 v[20:23], v[2:3], off
	global_load_dwordx4 v[24:27], v[2:3], off offset:1024
	global_load_dwordx2 v[28:29], v[6:7], off
	global_load_dwordx2 v[30:31], v[6:7], off offset:32
	v_lshl_add_u64 v[2:3], v[2:3], 0, s[8:9]
	v_lshl_add_u64 v[6:7], v[6:7], 0, s[8:9]
	ds_read_b128 v[184:187], v10 offset:5120
	ds_read_b128 v[192:195], v10 offset:7680
	ds_read_b128 v[188:191], v10 offset:5184
	ds_read_b128 v[196:199], v10 offset:7744
	s_waitcnt vmcnt(30)
	v_lshlrev_b32_e32 v200, 16, v40
	v_and_b32_e32 v201, 0xffff0000, v40
	v_lshlrev_b32_e32 v202, 16, v41
	v_and_b32_e32 v203, 0xffff0000, v41
	v_lshlrev_b32_e32 v204, 16, v42
	v_and_b32_e32 v205, 0xffff0000, v42
	v_lshlrev_b32_e32 v206, 16, v43
	v_and_b32_e32 v207, 0xffff0000, v43
	s_waitcnt lgkmcnt(2)
	v_mfma_f32_16x16x32_bf16 v[200:203], v[184:187], v[32:35], v[200:203]
	v_mfma_f32_16x16x32_bf16 v[204:207], v[192:195], v[32:35], v[204:207]
	s_waitcnt lgkmcnt(0)
	v_mfma_f32_16x16x32_bf16 v[200:203], v[188:191], v[36:39], v[200:203]
	v_mfma_f32_16x16x32_bf16 v[204:207], v[196:199], v[36:39], v[204:207]
	s_nop 6
	v_cvt_pk_bf16_f32 v200, v200, v201
	v_cvt_pk_bf16_f32 v201, v202, v203
	v_cvt_pk_bf16_f32 v204, v204, v205
	v_cvt_pk_bf16_f32 v205, v206, v207
	global_store_dwordx2 v[182:183], v[200:201], off
	global_store_dwordx2 v[182:183], v[204:205], off offset:32
	v_lshl_add_u64 v[182:183], v[182:183], 0, s[8:9]
	s_waitcnt lgkmcnt(0)
	s_barrier
	global_load_dwordx4 v[32:35], v[2:3], off
	global_load_dwordx4 v[36:39], v[2:3], off offset:1024
	global_load_dwordx2 v[40:41], v[6:7], off
	global_load_dwordx2 v[42:43], v[6:7], off offset:32
	v_lshl_add_u64 v[2:3], v[2:3], 0, s[8:9]
	v_lshl_add_u64 v[6:7], v[6:7], 0, s[8:9]
	ds_read_b128 v[184:187], v10
	ds_read_b128 v[192:195], v10 offset:2560
	ds_read_b128 v[188:191], v10 offset:64
	ds_read_b128 v[196:199], v10 offset:2624
	s_waitcnt vmcnt(32)
	v_lshlrev_b32_e32 v200, 16, v52
	v_and_b32_e32 v201, 0xffff0000, v52
	v_lshlrev_b32_e32 v202, 16, v53
	v_and_b32_e32 v203, 0xffff0000, v53
	v_lshlrev_b32_e32 v204, 16, v54
	v_and_b32_e32 v205, 0xffff0000, v54
	v_lshlrev_b32_e32 v206, 16, v55
	v_and_b32_e32 v207, 0xffff0000, v55
	s_waitcnt lgkmcnt(2)
	v_mfma_f32_16x16x32_bf16 v[200:203], v[184:187], v[44:47], v[200:203]
	v_mfma_f32_16x16x32_bf16 v[204:207], v[192:195], v[44:47], v[204:207]
	s_waitcnt lgkmcnt(0)
	v_mfma_f32_16x16x32_bf16 v[200:203], v[188:191], v[48:51], v[200:203]
	v_mfma_f32_16x16x32_bf16 v[204:207], v[196:199], v[48:51], v[204:207]
	s_nop 6
	v_cvt_pk_bf16_f32 v200, v200, v201
	v_cvt_pk_bf16_f32 v201, v202, v203
	v_cvt_pk_bf16_f32 v204, v204, v205
	v_cvt_pk_bf16_f32 v205, v206, v207
	global_store_dwordx2 v[182:183], v[200:201], off
	global_store_dwordx2 v[182:183], v[204:205], off offset:32
	v_lshl_add_u64 v[182:183], v[182:183], 0, s[8:9]
	s_waitcnt lgkmcnt(0)
	s_barrier
	global_load_dwordx4 v[44:47], v[2:3], off
	global_load_dwordx4 v[48:51], v[2:3], off offset:1024
	global_load_dwordx2 v[52:53], v[6:7], off
	global_load_dwordx2 v[54:55], v[6:7], off offset:32
	v_lshl_add_u64 v[2:3], v[2:3], 0, s[8:9]
	v_lshl_add_u64 v[6:7], v[6:7], 0, s[8:9]
	ds_read_b128 v[184:187], v10 offset:5120
	ds_read_b128 v[192:195], v10 offset:7680
	ds_read_b128 v[188:191], v10 offset:5184
	ds_read_b128 v[196:199], v10 offset:7744
	s_waitcnt vmcnt(34)
	v_lshlrev_b32_e32 v200, 16, v64
	v_and_b32_e32 v201, 0xffff0000, v64
	v_lshlrev_b32_e32 v202, 16, v65
	v_and_b32_e32 v203, 0xffff0000, v65
	v_lshlrev_b32_e32 v204, 16, v66
	v_and_b32_e32 v205, 0xffff0000, v66
	v_lshlrev_b32_e32 v206, 16, v67
	v_and_b32_e32 v207, 0xffff0000, v67
	s_waitcnt lgkmcnt(2)
	v_mfma_f32_16x16x32_bf16 v[200:203], v[184:187], v[56:59], v[200:203]
	v_mfma_f32_16x16x32_bf16 v[204:207], v[192:195], v[56:59], v[204:207]
	s_waitcnt lgkmcnt(0)
	v_mfma_f32_16x16x32_bf16 v[200:203], v[188:191], v[60:63], v[200:203]
	v_mfma_f32_16x16x32_bf16 v[204:207], v[196:199], v[60:63], v[204:207]
	s_nop 6
	v_cvt_pk_bf16_f32 v200, v200, v201
	v_cvt_pk_bf16_f32 v201, v202, v203
	v_cvt_pk_bf16_f32 v204, v204, v205
	v_cvt_pk_bf16_f32 v205, v206, v207
	global_store_dwordx2 v[182:183], v[200:201], off
	global_store_dwordx2 v[182:183], v[204:205], off offset:32
	v_lshl_add_u64 v[182:183], v[182:183], 0, s[8:9]
	s_waitcnt lgkmcnt(0)
	s_barrier
	global_load_dwordx4 v[56:59], v[2:3], off
	global_load_dwordx4 v[60:63], v[2:3], off offset:1024
	global_load_dwordx2 v[64:65], v[6:7], off
	global_load_dwordx2 v[66:67], v[6:7], off offset:32
	v_lshl_add_u64 v[2:3], v[2:3], 0, s[8:9]
	v_lshl_add_u64 v[6:7], v[6:7], 0, s[8:9]
	ds_read_b128 v[184:187], v10
	ds_read_b128 v[192:195], v10 offset:2560
	ds_read_b128 v[188:191], v10 offset:64
	ds_read_b128 v[196:199], v10 offset:2624
	s_waitcnt vmcnt(36)
	v_lshlrev_b32_e32 v200, 16, v76
	v_and_b32_e32 v201, 0xffff0000, v76
	v_lshlrev_b32_e32 v202, 16, v77
	v_and_b32_e32 v203, 0xffff0000, v77
	v_lshlrev_b32_e32 v204, 16, v78
	v_and_b32_e32 v205, 0xffff0000, v78
	v_lshlrev_b32_e32 v206, 16, v79
	v_and_b32_e32 v207, 0xffff0000, v79
	s_waitcnt lgkmcnt(2)
	v_mfma_f32_16x16x32_bf16 v[200:203], v[184:187], v[68:71], v[200:203]
	v_mfma_f32_16x16x32_bf16 v[204:207], v[192:195], v[68:71], v[204:207]
	s_waitcnt lgkmcnt(0)
	v_mfma_f32_16x16x32_bf16 v[200:203], v[188:191], v[72:75], v[200:203]
	v_mfma_f32_16x16x32_bf16 v[204:207], v[196:199], v[72:75], v[204:207]
	s_nop 6
	v_cvt_pk_bf16_f32 v200, v200, v201
	v_cvt_pk_bf16_f32 v201, v202, v203
	v_cvt_pk_bf16_f32 v204, v204, v205
	v_cvt_pk_bf16_f32 v205, v206, v207
	global_store_dwordx2 v[182:183], v[200:201], off
	global_store_dwordx2 v[182:183], v[204:205], off offset:32
	v_lshl_add_u64 v[182:183], v[182:183], 0, s[8:9]
	s_waitcnt lgkmcnt(0)
	s_barrier
	global_load_dwordx4 v[68:71], v[2:3], off
	global_load_dwordx4 v[72:75], v[2:3], off offset:1024
	global_load_dwordx2 v[76:77], v[6:7], off
	global_load_dwordx2 v[78:79], v[6:7], off offset:32
	v_lshl_add_u64 v[2:3], v[2:3], 0, s[8:9]
	v_lshl_add_u64 v[6:7], v[6:7], 0, s[8:9]
	ds_read_b128 v[184:187], v10 offset:5120
	ds_read_b128 v[192:195], v10 offset:7680
	ds_read_b128 v[188:191], v10 offset:5184
	ds_read_b128 v[196:199], v10 offset:7744
	s_waitcnt vmcnt(38)
	v_lshlrev_b32_e32 v200, 16, v88
	v_and_b32_e32 v201, 0xffff0000, v88
	v_lshlrev_b32_e32 v202, 16, v89
	v_and_b32_e32 v203, 0xffff0000, v89
	v_lshlrev_b32_e32 v204, 16, v90
	v_and_b32_e32 v205, 0xffff0000, v90
	v_lshlrev_b32_e32 v206, 16, v91
	v_and_b32_e32 v207, 0xffff0000, v91
	s_waitcnt lgkmcnt(2)
	v_mfma_f32_16x16x32_bf16 v[200:203], v[184:187], v[80:83], v[200:203]
	v_mfma_f32_16x16x32_bf16 v[204:207], v[192:195], v[80:83], v[204:207]
	s_waitcnt lgkmcnt(0)
	v_mfma_f32_16x16x32_bf16 v[200:203], v[188:191], v[84:87], v[200:203]
	v_mfma_f32_16x16x32_bf16 v[204:207], v[196:199], v[84:87], v[204:207]
	s_nop 6
	v_cvt_pk_bf16_f32 v200, v200, v201
	v_cvt_pk_bf16_f32 v201, v202, v203
	v_cvt_pk_bf16_f32 v204, v204, v205
	v_cvt_pk_bf16_f32 v205, v206, v207
	global_store_dwordx2 v[182:183], v[200:201], off
	global_store_dwordx2 v[182:183], v[204:205], off offset:32
	v_lshl_add_u64 v[182:183], v[182:183], 0, s[8:9]
	s_waitcnt lgkmcnt(0)
	s_barrier
	global_load_dwordx4 v[80:83], v[2:3], off
	global_load_dwordx4 v[84:87], v[2:3], off offset:1024
	global_load_dwordx2 v[88:89], v[6:7], off
	global_load_dwordx2 v[90:91], v[6:7], off offset:32
	v_lshl_add_u64 v[2:3], v[2:3], 0, s[8:9]
	v_lshl_add_u64 v[6:7], v[6:7], 0, s[8:9]
	ds_read_b128 v[184:187], v10
	ds_read_b128 v[192:195], v10 offset:2560
	ds_read_b128 v[188:191], v10 offset:64
	ds_read_b128 v[196:199], v10 offset:2624
	s_waitcnt vmcnt(40)
	v_lshlrev_b32_e32 v200, 16, v100
	v_and_b32_e32 v201, 0xffff0000, v100
	v_lshlrev_b32_e32 v202, 16, v101
	v_and_b32_e32 v203, 0xffff0000, v101
	v_lshlrev_b32_e32 v204, 16, v102
	v_and_b32_e32 v205, 0xffff0000, v102
	v_lshlrev_b32_e32 v206, 16, v103
	v_and_b32_e32 v207, 0xffff0000, v103
	s_waitcnt lgkmcnt(2)
	v_mfma_f32_16x16x32_bf16 v[200:203], v[184:187], v[92:95], v[200:203]
	v_mfma_f32_16x16x32_bf16 v[204:207], v[192:195], v[92:95], v[204:207]
	s_waitcnt lgkmcnt(0)
	v_mfma_f32_16x16x32_bf16 v[200:203], v[188:191], v[96:99], v[200:203]
	v_mfma_f32_16x16x32_bf16 v[204:207], v[196:199], v[96:99], v[204:207]
	s_nop 6
	v_cvt_pk_bf16_f32 v200, v200, v201
	v_cvt_pk_bf16_f32 v201, v202, v203
	v_cvt_pk_bf16_f32 v204, v204, v205
	v_cvt_pk_bf16_f32 v205, v206, v207
	global_store_dwordx2 v[182:183], v[200:201], off
	global_store_dwordx2 v[182:183], v[204:205], off offset:32
	v_lshl_add_u64 v[182:183], v[182:183], 0, s[8:9]
	s_waitcnt lgkmcnt(0)
	s_barrier
	global_load_dwordx4 v[92:95], v[2:3], off
	global_load_dwordx4 v[96:99], v[2:3], off offset:1024
	global_load_dwordx2 v[100:101], v[6:7], off
	global_load_dwordx2 v[102:103], v[6:7], off offset:32
	v_lshl_add_u64 v[2:3], v[2:3], 0, s[8:9]
	v_lshl_add_u64 v[6:7], v[6:7], 0, s[8:9]
	ds_read_b128 v[184:187], v10 offset:5120
	ds_read_b128 v[192:195], v10 offset:7680
	ds_read_b128 v[188:191], v10 offset:5184
	ds_read_b128 v[196:199], v10 offset:7744
	s_waitcnt vmcnt(42)
	v_lshlrev_b32_e32 v200, 16, v112
	v_and_b32_e32 v201, 0xffff0000, v112
	v_lshlrev_b32_e32 v202, 16, v113
	v_and_b32_e32 v203, 0xffff0000, v113
	v_lshlrev_b32_e32 v204, 16, v114
	v_and_b32_e32 v205, 0xffff0000, v114
	v_lshlrev_b32_e32 v206, 16, v115
	v_and_b32_e32 v207, 0xffff0000, v115
	s_waitcnt lgkmcnt(2)
	v_mfma_f32_16x16x32_bf16 v[200:203], v[184:187], v[104:107], v[200:203]
	v_mfma_f32_16x16x32_bf16 v[204:207], v[192:195], v[104:107], v[204:207]
	s_waitcnt lgkmcnt(0)
	v_mfma_f32_16x16x32_bf16 v[200:203], v[188:191], v[108:111], v[200:203]
	v_mfma_f32_16x16x32_bf16 v[204:207], v[196:199], v[108:111], v[204:207]
	s_nop 6
	v_cvt_pk_bf16_f32 v200, v200, v201
	v_cvt_pk_bf16_f32 v201, v202, v203
	v_cvt_pk_bf16_f32 v204, v204, v205
	v_cvt_pk_bf16_f32 v205, v206, v207
	global_store_dwordx2 v[182:183], v[200:201], off
	global_store_dwordx2 v[182:183], v[204:205], off offset:32
	v_lshl_add_u64 v[182:183], v[182:183], 0, s[8:9]
	s_waitcnt lgkmcnt(0)
	s_barrier
	s_mov_b32 s10, 6
.Lsp_loop0:
	global_load_dwordx4 v[104:107], v[2:3], off
	global_load_dwordx4 v[108:111], v[2:3], off offset:1024
	global_load_dwordx2 v[112:113], v[6:7], off
	global_load_dwordx2 v[114:115], v[6:7], off offset:32
	v_lshl_add_u64 v[2:3], v[2:3], 0, s[8:9]
	v_lshl_add_u64 v[6:7], v[6:7], 0, s[8:9]
	ds_read_b128 v[184:187], v10
	ds_read_b128 v[192:195], v10 offset:2560
	ds_read_b128 v[188:191], v10 offset:64
	ds_read_b128 v[196:199], v10 offset:2624
	s_waitcnt vmcnt(42)
	v_lshlrev_b32_e32 v200, 16, v28
	v_and_b32_e32 v201, 0xffff0000, v28
	v_lshlrev_b32_e32 v202, 16, v29
	v_and_b32_e32 v203, 0xffff0000, v29
	v_lshlrev_b32_e32 v204, 16, v30
	v_and_b32_e32 v205, 0xffff0000, v30
	v_lshlrev_b32_e32 v206, 16, v31
	v_and_b32_e32 v207, 0xffff0000, v31
	s_waitcnt lgkmcnt(2)
	v_mfma_f32_16x16x32_bf16 v[200:203], v[184:187], v[20:23], v[200:203]
	v_mfma_f32_16x16x32_bf16 v[204:207], v[192:195], v[20:23], v[204:207]
	s_waitcnt lgkmcnt(0)
	v_mfma_f32_16x16x32_bf16 v[200:203], v[188:191], v[24:27], v[200:203]
	v_mfma_f32_16x16x32_bf16 v[204:207], v[196:199], v[24:27], v[204:207]
	s_nop 6
	v_cvt_pk_bf16_f32 v200, v200, v201
	v_cvt_pk_bf16_f32 v201, v202, v203
	v_cvt_pk_bf16_f32 v204, v204, v205
	v_cvt_pk_bf16_f32 v205, v206, v207
	global_store_dwordx2 v[182:183], v[200:201], off
	global_store_dwordx2 v[182:183], v[204:205], off offset:32
	v_lshl_add_u64 v[182:183], v[182:183], 0, s[8:9]
	s_waitcnt lgkmcnt(0)
	s_barrier
	global_load_dwordx4 v[20:23], v[2:3], off
	global_load_dwordx4 v[24:27], v[2:3], off offset:1024
	global_load_dwordx2 v[28:29], v[6:7], off
	global_load_dwordx2 v[30:31], v[6:7], off offset:32
	v_lshl_add_u64 v[2:3], v[2:3], 0, s[8:9]
	v_lshl_add_u64 v[6:7], v[6:7], 0, s[8:9]
	ds_read_b128 v[184:187], v10 offset:5120
	ds_read_b128 v[192:195], v10 offset:7680
	ds_read_b128 v[188:191], v10 offset:5184
	ds_read_b128 v[196:199], v10 offset:7744
	s_waitcnt vmcnt(42)
	v_lshlrev_b32_e32 v200, 16, v40
	v_and_b32_e32 v201, 0xffff0000, v40
	v_lshlrev_b32_e32 v202, 16, v41
	v_and_b32_e32 v203, 0xffff0000, v41
	v_lshlrev_b32_e32 v204, 16, v42
	v_and_b32_e32 v205, 0xffff0000, v42
	v_lshlrev_b32_e32 v206, 16, v43
	v_and_b32_e32 v207, 0xffff0000, v43
	s_waitcnt lgkmcnt(2)
	v_mfma_f32_16x16x32_bf16 v[200:203], v[184:187], v[32:35], v[200:203]
	v_mfma_f32_16x16x32_bf16 v[204:207], v[192:195], v[32:35], v[204:207]
	s_waitcnt lgkmcnt(0)
	v_mfma_f32_16x16x32_bf16 v[200:203], v[188:191], v[36:39], v[200:203]
	v_mfma_f32_16x16x32_bf16 v[204:207], v[196:199], v[36:39], v[204:207]
	s_nop 6
	v_cvt_pk_bf16_f32 v200, v200, v201
	v_cvt_pk_bf16_f32 v201, v202, v203
	v_cvt_pk_bf16_f32 v204, v204, v205
	v_cvt_pk_bf16_f32 v205, v206, v207
	global_store_dwordx2 v[182:183], v[200:201], off
	global_store_dwordx2 v[182:183], v[204:205], off offset:32
	v_lshl_add_u64 v[182:183], v[182:183], 0, s[8:9]
	s_waitcnt lgkmcnt(0)
	s_barrier
	global_load_dwordx4 v[32:35], v[2:3], off
	global_load_dwordx4 v[36:39], v[2:3], off offset:1024
	global_load_dwordx2 v[40:41], v[6:7], off
	global_load_dwordx2 v[42:43], v[6:7], off offset:32
	v_lshl_add_u64 v[2:3], v[2:3], 0, s[8:9]
	v_lshl_add_u64 v[6:7], v[6:7], 0, s[8:9]
	ds_read_b128 v[184:187], v10
	ds_read_b128 v[192:195], v10 offset:2560
	ds_read_b128 v[188:191], v10 offset:64
	ds_read_b128 v[196:199], v10 offset:2624
	s_waitcnt vmcnt(42)
	v_lshlrev_b32_e32 v200, 16, v52
	v_and_b32_e32 v201, 0xffff0000, v52
	v_lshlrev_b32_e32 v202, 16, v53
	v_and_b32_e32 v203, 0xffff0000, v53
	v_lshlrev_b32_e32 v204, 16, v54
	v_and_b32_e32 v205, 0xffff0000, v54
	v_lshlrev_b32_e32 v206, 16, v55
	v_and_b32_e32 v207, 0xffff0000, v55
	s_waitcnt lgkmcnt(2)
	v_mfma_f32_16x16x32_bf16 v[200:203], v[184:187], v[44:47], v[200:203]
	v_mfma_f32_16x16x32_bf16 v[204:207], v[192:195], v[44:47], v[204:207]
	s_waitcnt lgkmcnt(0)
	v_mfma_f32_16x16x32_bf16 v[200:203], v[188:191], v[48:51], v[200:203]
	v_mfma_f32_16x16x32_bf16 v[204:207], v[196:199], v[48:51], v[204:207]
	s_nop 6
	v_cvt_pk_bf16_f32 v200, v200, v201
	v_cvt_pk_bf16_f32 v201, v202, v203
	v_cvt_pk_bf16_f32 v204, v204, v205
	v_cvt_pk_bf16_f32 v205, v206, v207
	global_store_dwordx2 v[182:183], v[200:201], off
	global_store_dwordx2 v[182:183], v[204:205], off offset:32
	v_lshl_add_u64 v[182:183], v[182:183], 0, s[8:9]
	s_waitcnt lgkmcnt(0)
	s_barrier
	global_load_dwordx4 v[44:47], v[2:3], off
	global_load_dwordx4 v[48:51], v[2:3], off offset:1024
	global_load_dwordx2 v[52:53], v[6:7], off
	global_load_dwordx2 v[54:55], v[6:7], off offset:32
	v_lshl_add_u64 v[2:3], v[2:3], 0, s[8:9]
	v_lshl_add_u64 v[6:7], v[6:7], 0, s[8:9]
	ds_read_b128 v[184:187], v10 offset:5120
	ds_read_b128 v[192:195], v10 offset:7680
	ds_read_b128 v[188:191], v10 offset:5184
	ds_read_b128 v[196:199], v10 offset:7744
	s_waitcnt vmcnt(42)
	v_lshlrev_b32_e32 v200, 16, v64
	v_and_b32_e32 v201, 0xffff0000, v64
	v_lshlrev_b32_e32 v202, 16, v65
	v_and_b32_e32 v203, 0xffff0000, v65
	v_lshlrev_b32_e32 v204, 16, v66
	v_and_b32_e32 v205, 0xffff0000, v66
	v_lshlrev_b32_e32 v206, 16, v67
	v_and_b32_e32 v207, 0xffff0000, v67
	s_waitcnt lgkmcnt(2)
	v_mfma_f32_16x16x32_bf16 v[200:203], v[184:187], v[56:59], v[200:203]
	v_mfma_f32_16x16x32_bf16 v[204:207], v[192:195], v[56:59], v[204:207]
	s_waitcnt lgkmcnt(0)
	v_mfma_f32_16x16x32_bf16 v[200:203], v[188:191], v[60:63], v[200:203]
	v_mfma_f32_16x16x32_bf16 v[204:207], v[196:199], v[60:63], v[204:207]
	s_nop 6
	v_cvt_pk_bf16_f32 v200, v200, v201
	v_cvt_pk_bf16_f32 v201, v202, v203
	v_cvt_pk_bf16_f32 v204, v204, v205
	v_cvt_pk_bf16_f32 v205, v206, v207
	global_store_dwordx2 v[182:183], v[200:201], off
	global_store_dwordx2 v[182:183], v[204:205], off offset:32
	v_lshl_add_u64 v[182:183], v[182:183], 0, s[8:9]
	s_waitcnt lgkmcnt(0)
	s_barrier
	global_load_dwordx4 v[56:59], v[2:3], off
	global_load_dwordx4 v[60:63], v[2:3], off offset:1024
	global_load_dwordx2 v[64:65], v[6:7], off
	global_load_dwordx2 v[66:67], v[6:7], off offset:32
	v_lshl_add_u64 v[2:3], v[2:3], 0, s[8:9]
	v_lshl_add_u64 v[6:7], v[6:7], 0, s[8:9]
	ds_read_b128 v[184:187], v10
	ds_read_b128 v[192:195], v10 offset:2560
	ds_read_b128 v[188:191], v10 offset:64
	ds_read_b128 v[196:199], v10 offset:2624
	s_waitcnt vmcnt(42)
	v_lshlrev_b32_e32 v200, 16, v76
	v_and_b32_e32 v201, 0xffff0000, v76
	v_lshlrev_b32_e32 v202, 16, v77
	v_and_b32_e32 v203, 0xffff0000, v77
	v_lshlrev_b32_e32 v204, 16, v78
	v_and_b32_e32 v205, 0xffff0000, v78
	v_lshlrev_b32_e32 v206, 16, v79
	v_and_b32_e32 v207, 0xffff0000, v79
	s_waitcnt lgkmcnt(2)
	v_mfma_f32_16x16x32_bf16 v[200:203], v[184:187], v[68:71], v[200:203]
	v_mfma_f32_16x16x32_bf16 v[204:207], v[192:195], v[68:71], v[204:207]
	s_waitcnt lgkmcnt(0)
	v_mfma_f32_16x16x32_bf16 v[200:203], v[188:191], v[72:75], v[200:203]
	v_mfma_f32_16x16x32_bf16 v[204:207], v[196:199], v[72:75], v[204:207]
	s_nop 6
	v_cvt_pk_bf16_f32 v200, v200, v201
	v_cvt_pk_bf16_f32 v201, v202, v203
	v_cvt_pk_bf16_f32 v204, v204, v205
	v_cvt_pk_bf16_f32 v205, v206, v207
	global_store_dwordx2 v[182:183], v[200:201], off
	global_store_dwordx2 v[182:183], v[204:205], off offset:32
	v_lshl_add_u64 v[182:183], v[182:183], 0, s[8:9]
	s_waitcnt lgkmcnt(0)
	s_barrier
	global_load_dwordx4 v[68:71], v[2:3], off
	global_load_dwordx4 v[72:75], v[2:3], off offset:1024
	global_load_dwordx2 v[76:77], v[6:7], off
	global_load_dwordx2 v[78:79], v[6:7], off offset:32
	v_lshl_add_u64 v[2:3], v[2:3], 0, s[8:9]
	v_lshl_add_u64 v[6:7], v[6:7], 0, s[8:9]
	ds_read_b128 v[184:187], v10 offset:5120
	ds_read_b128 v[192:195], v10 offset:7680
	ds_read_b128 v[188:191], v10 offset:5184
	ds_read_b128 v[196:199], v10 offset:7744
	s_waitcnt vmcnt(42)
	v_lshlrev_b32_e32 v200, 16, v88
	v_and_b32_e32 v201, 0xffff0000, v88
	v_lshlrev_b32_e32 v202, 16, v89
	v_and_b32_e32 v203, 0xffff0000, v89
	v_lshlrev_b32_e32 v204, 16, v90
	v_and_b32_e32 v205, 0xffff0000, v90
	v_lshlrev_b32_e32 v206, 16, v91
	v_and_b32_e32 v207, 0xffff0000, v91
	s_waitcnt lgkmcnt(2)
	v_mfma_f32_16x16x32_bf16 v[200:203], v[184:187], v[80:83], v[200:203]
	v_mfma_f32_16x16x32_bf16 v[204:207], v[192:195], v[80:83], v[204:207]
	s_waitcnt lgkmcnt(0)
	v_mfma_f32_16x16x32_bf16 v[200:203], v[188:191], v[84:87], v[200:203]
	v_mfma_f32_16x16x32_bf16 v[204:207], v[196:199], v[84:87], v[204:207]
	s_nop 6
	v_cvt_pk_bf16_f32 v200, v200, v201
	v_cvt_pk_bf16_f32 v201, v202, v203
	v_cvt_pk_bf16_f32 v204, v204, v205
	v_cvt_pk_bf16_f32 v205, v206, v207
	global_store_dwordx2 v[182:183], v[200:201], off
	global_store_dwordx2 v[182:183], v[204:205], off offset:32
	v_lshl_add_u64 v[182:183], v[182:183], 0, s[8:9]
	s_waitcnt lgkmcnt(0)
	s_barrier
	global_load_dwordx4 v[80:83], v[2:3], off
	global_load_dwordx4 v[84:87], v[2:3], off offset:1024
	global_load_dwordx2 v[88:89], v[6:7], off
	global_load_dwordx2 v[90:91], v[6:7], off offset:32
	v_lshl_add_u64 v[2:3], v[2:3], 0, s[8:9]
	v_lshl_add_u64 v[6:7], v[6:7], 0, s[8:9]
	ds_read_b128 v[184:187], v10
	ds_read_b128 v[192:195], v10 offset:2560
	ds_read_b128 v[188:191], v10 offset:64
	ds_read_b128 v[196:199], v10 offset:2624
	s_waitcnt vmcnt(42)
	v_lshlrev_b32_e32 v200, 16, v100
	v_and_b32_e32 v201, 0xffff0000, v100
	v_lshlrev_b32_e32 v202, 16, v101
	v_and_b32_e32 v203, 0xffff0000, v101
	v_lshlrev_b32_e32 v204, 16, v102
	v_and_b32_e32 v205, 0xffff0000, v102
	v_lshlrev_b32_e32 v206, 16, v103
	v_and_b32_e32 v207, 0xffff0000, v103
	s_waitcnt lgkmcnt(2)
	v_mfma_f32_16x16x32_bf16 v[200:203], v[184:187], v[92:95], v[200:203]
	v_mfma_f32_16x16x32_bf16 v[204:207], v[192:195], v[92:95], v[204:207]
	s_waitcnt lgkmcnt(0)
	v_mfma_f32_16x16x32_bf16 v[200:203], v[188:191], v[96:99], v[200:203]
	v_mfma_f32_16x16x32_bf16 v[204:207], v[196:199], v[96:99], v[204:207]
	s_nop 6
	v_cvt_pk_bf16_f32 v200, v200, v201
	v_cvt_pk_bf16_f32 v201, v202, v203
	v_cvt_pk_bf16_f32 v204, v204, v205
	v_cvt_pk_bf16_f32 v205, v206, v207
	global_store_dwordx2 v[182:183], v[200:201], off
	global_store_dwordx2 v[182:183], v[204:205], off offset:32
	v_lshl_add_u64 v[182:183], v[182:183], 0, s[8:9]
	s_waitcnt lgkmcnt(0)
	s_barrier
	global_load_dwordx4 v[92:95], v[2:3], off
	global_load_dwordx4 v[96:99], v[2:3], off offset:1024
	global_load_dwordx2 v[100:101], v[6:7], off
	global_load_dwordx2 v[102:103], v[6:7], off offset:32
	v_lshl_add_u64 v[2:3], v[2:3], 0, s[8:9]
	v_lshl_add_u64 v[6:7], v[6:7], 0, s[8:9]
	ds_read_b128 v[184:187], v10 offset:5120
	ds_read_b128 v[192:195], v10 offset:7680
	ds_read_b128 v[188:191], v10 offset:5184
	ds_read_b128 v[196:199], v10 offset:7744
	s_waitcnt vmcnt(42)
	v_lshlrev_b32_e32 v200, 16, v112
	v_and_b32_e32 v201, 0xffff0000, v112
	v_lshlrev_b32_e32 v202, 16, v113
	v_and_b32_e32 v203, 0xffff0000, v113
	v_lshlrev_b32_e32 v204, 16, v114
	v_and_b32_e32 v205, 0xffff0000, v114
	v_lshlrev_b32_e32 v206, 16, v115
	v_and_b32_e32 v207, 0xffff0000, v115
	s_waitcnt lgkmcnt(2)
	v_mfma_f32_16x16x32_bf16 v[200:203], v[184:187], v[104:107], v[200:203]
	v_mfma_f32_16x16x32_bf16 v[204:207], v[192:195], v[104:107], v[204:207]
	s_waitcnt lgkmcnt(0)
	v_mfma_f32_16x16x32_bf16 v[200:203], v[188:191], v[108:111], v[200:203]
	v_mfma_f32_16x16x32_bf16 v[204:207], v[196:199], v[108:111], v[204:207]
	s_nop 6
	v_cvt_pk_bf16_f32 v200, v200, v201
	v_cvt_pk_bf16_f32 v201, v202, v203
	v_cvt_pk_bf16_f32 v204, v204, v205
	v_cvt_pk_bf16_f32 v205, v206, v207
	global_store_dwordx2 v[182:183], v[200:201], off
	global_store_dwordx2 v[182:183], v[204:205], off offset:32
	v_lshl_add_u64 v[182:183], v[182:183], 0, s[8:9]
	s_waitcnt lgkmcnt(0)
	s_barrier
	s_add_i32 s10, s10, -1
	s_cmp_lg_u32 s10, 0
	s_cbranch_scc1 .Lsp_loop0
	global_load_dwordx4 v[104:107], v[2:3], off
	global_load_dwordx4 v[108:111], v[2:3], off offset:1024
	global_load_dwordx2 v[112:113], v[6:7], off
	global_load_dwordx2 v[114:115], v[6:7], off offset:32
	v_lshl_add_u64 v[2:3], v[2:3], 0, s[8:9]
	v_lshl_add_u64 v[6:7], v[6:7], 0, s[8:9]
	ds_read_b128 v[184:187], v10
	ds_read_b128 v[192:195], v10 offset:2560
	ds_read_b128 v[188:191], v10 offset:64
	ds_read_b128 v[196:199], v10 offset:2624
	s_waitcnt vmcnt(42)
	v_lshlrev_b32_e32 v200, 16, v28
	v_and_b32_e32 v201, 0xffff0000, v28
	v_lshlrev_b32_e32 v202, 16, v29
	v_and_b32_e32 v203, 0xffff0000, v29
	v_lshlrev_b32_e32 v204, 16, v30
	v_and_b32_e32 v205, 0xffff0000, v30
	v_lshlrev_b32_e32 v206, 16, v31
	v_and_b32_e32 v207, 0xffff0000, v31
	s_waitcnt lgkmcnt(2)
	v_mfma_f32_16x16x32_bf16 v[200:203], v[184:187], v[20:23], v[200:203]
	v_mfma_f32_16x16x32_bf16 v[204:207], v[192:195], v[20:23], v[204:207]
	s_waitcnt lgkmcnt(0)
	v_mfma_f32_16x16x32_bf16 v[200:203], v[188:191], v[24:27], v[200:203]
	v_mfma_f32_16x16x32_bf16 v[204:207], v[196:199], v[24:27], v[204:207]
	s_nop 6
	v_cvt_pk_bf16_f32 v200, v200, v201
	v_cvt_pk_bf16_f32 v201, v202, v203
	v_cvt_pk_bf16_f32 v204, v204, v205
	v_cvt_pk_bf16_f32 v205, v206, v207
	global_store_dwordx2 v[182:183], v[200:201], off
	global_store_dwordx2 v[182:183], v[204:205], off offset:32
	v_lshl_add_u64 v[182:183], v[182:183], 0, s[8:9]
	s_waitcnt lgkmcnt(0)
	s_barrier
	ds_read_b128 v[184:187], v10 offset:5120
	ds_read_b128 v[192:195], v10 offset:7680
	ds_read_b128 v[188:191], v10 offset:5184
	ds_read_b128 v[196:199], v10 offset:7744
	s_waitcnt vmcnt(38)
	v_lshlrev_b32_e32 v200, 16, v40
	v_and_b32_e32 v201, 0xffff0000, v40
	v_lshlrev_b32_e32 v202, 16, v41
	v_and_b32_e32 v203, 0xffff0000, v41
	v_lshlrev_b32_e32 v204, 16, v42
	v_and_b32_e32 v205, 0xffff0000, v42
	v_lshlrev_b32_e32 v206, 16, v43
	v_and_b32_e32 v207, 0xffff0000, v43
	s_waitcnt lgkmcnt(2)
	v_mfma_f32_16x16x32_bf16 v[200:203], v[184:187], v[32:35], v[200:203]
	v_mfma_f32_16x16x32_bf16 v[204:207], v[192:195], v[32:35], v[204:207]
	s_waitcnt lgkmcnt(0)
	v_mfma_f32_16x16x32_bf16 v[200:203], v[188:191], v[36:39], v[200:203]
	v_mfma_f32_16x16x32_bf16 v[204:207], v[196:199], v[36:39], v[204:207]
	s_nop 6
	v_cvt_pk_bf16_f32 v200, v200, v201
	v_cvt_pk_bf16_f32 v201, v202, v203
	v_cvt_pk_bf16_f32 v204, v204, v205
	v_cvt_pk_bf16_f32 v205, v206, v207
	global_store_dwordx2 v[182:183], v[200:201], off
	global_store_dwordx2 v[182:183], v[204:205], off offset:32
	v_lshl_add_u64 v[182:183], v[182:183], 0, s[8:9]
	s_waitcnt lgkmcnt(0)
	s_barrier
	ds_read_b128 v[184:187], v10
	ds_read_b128 v[192:195], v10 offset:2560
	ds_read_b128 v[188:191], v10 offset:64
	ds_read_b128 v[196:199], v10 offset:2624
	s_waitcnt vmcnt(34)
	v_lshlrev_b32_e32 v200, 16, v52
	v_and_b32_e32 v201, 0xffff0000, v52
	v_lshlrev_b32_e32 v202, 16, v53
	v_and_b32_e32 v203, 0xffff0000, v53
	v_lshlrev_b32_e32 v204, 16, v54
	v_and_b32_e32 v205, 0xffff0000, v54
	v_lshlrev_b32_e32 v206, 16, v55
	v_and_b32_e32 v207, 0xffff0000, v55
	s_waitcnt lgkmcnt(2)
	v_mfma_f32_16x16x32_bf16 v[200:203], v[184:187], v[44:47], v[200:203]
	v_mfma_f32_16x16x32_bf16 v[204:207], v[192:195], v[44:47], v[204:207]
	s_waitcnt lgkmcnt(0)
	v_mfma_f32_16x16x32_bf16 v[200:203], v[188:191], v[48:51], v[200:203]
	v_mfma_f32_16x16x32_bf16 v[204:207], v[196:199], v[48:51], v[204:207]
	s_nop 6
	v_cvt_pk_bf16_f32 v200, v200, v201
	v_cvt_pk_bf16_f32 v201, v202, v203
	v_cvt_pk_bf16_f32 v204, v204, v205
	v_cvt_pk_bf16_f32 v205, v206, v207
	global_store_dwordx2 v[182:183], v[200:201], off
	global_store_dwordx2 v[182:183], v[204:205], off offset:32
	v_lshl_add_u64 v[182:183], v[182:183], 0, s[8:9]
	s_waitcnt lgkmcnt(0)
	s_barrier
	ds_read_b128 v[184:187], v10 offset:5120
	ds_read_b128 v[192:195], v10 offset:7680
	ds_read_b128 v[188:191], v10 offset:5184
	ds_read_b128 v[196:199], v10 offset:7744
	s_waitcnt vmcnt(30)
	v_lshlrev_b32_e32 v200, 16, v64
	v_and_b32_e32 v201, 0xffff0000, v64
	v_lshlrev_b32_e32 v202, 16, v65
	v_and_b32_e32 v203, 0xffff0000, v65
	v_lshlrev_b32_e32 v204, 16, v66
	v_and_b32_e32 v205, 0xffff0000, v66
	v_lshlrev_b32_e32 v206, 16, v67
	v_and_b32_e32 v207, 0xffff0000, v67
	s_waitcnt lgkmcnt(2)
	v_mfma_f32_16x16x32_bf16 v[200:203], v[184:187], v[56:59], v[200:203]
	v_mfma_f32_16x16x32_bf16 v[204:207], v[192:195], v[56:59], v[204:207]
	s_waitcnt lgkmcnt(0)
	v_mfma_f32_16x16x32_bf16 v[200:203], v[188:191], v[60:63], v[200:203]
	v_mfma_f32_16x16x32_bf16 v[204:207], v[196:199], v[60:63], v[204:207]
	s_nop 6
	v_cvt_pk_bf16_f32 v200, v200, v201
	v_cvt_pk_bf16_f32 v201, v202, v203
	v_cvt_pk_bf16_f32 v204, v204, v205
	v_cvt_pk_bf16_f32 v205, v206, v207
	global_store_dwordx2 v[182:183], v[200:201], off
	global_store_dwordx2 v[182:183], v[204:205], off offset:32
	v_lshl_add_u64 v[182:183], v[182:183], 0, s[8:9]
	s_waitcnt lgkmcnt(0)
	s_barrier
	ds_read_b128 v[184:187], v10
	ds_read_b128 v[192:195], v10 offset:2560
	ds_read_b128 v[188:191], v10 offset:64
	ds_read_b128 v[196:199], v10 offset:2624
	s_waitcnt vmcnt(26)
	v_lshlrev_b32_e32 v200, 16, v76
	v_and_b32_e32 v201, 0xffff0000, v76
	v_lshlrev_b32_e32 v202, 16, v77
	v_and_b32_e32 v203, 0xffff0000, v77
	v_lshlrev_b32_e32 v204, 16, v78
	v_and_b32_e32 v205, 0xffff0000, v78
	v_lshlrev_b32_e32 v206, 16, v79
	v_and_b32_e32 v207, 0xffff0000, v79
	s_waitcnt lgkmcnt(2)
	v_mfma_f32_16x16x32_bf16 v[200:203], v[184:187], v[68:71], v[200:203]
	v_mfma_f32_16x16x32_bf16 v[204:207], v[192:195], v[68:71], v[204:207]
	s_waitcnt lgkmcnt(0)
	v_mfma_f32_16x16x32_bf16 v[200:203], v[188:191], v[72:75], v[200:203]
	v_mfma_f32_16x16x32_bf16 v[204:207], v[196:199], v[72:75], v[204:207]
	s_nop 6
	v_cvt_pk_bf16_f32 v200, v200, v201
	v_cvt_pk_bf16_f32 v201, v202, v203
	v_cvt_pk_bf16_f32 v204, v204, v205
	v_cvt_pk_bf16_f32 v205, v206, v207
	global_store_dwordx2 v[182:183], v[200:201], off
	global_store_dwordx2 v[182:183], v[204:205], off offset:32
	v_lshl_add_u64 v[182:183], v[182:183], 0, s[8:9]
	s_waitcnt lgkmcnt(0)
	s_barrier
	ds_read_b128 v[184:187], v10 offset:5120
	ds_read_b128 v[192:195], v10 offset:7680
	ds_read_b128 v[188:191], v10 offset:5184
	ds_read_b128 v[196:199], v10 offset:7744
	s_waitcnt vmcnt(22)
	v_lshlrev_b32_e32 v200, 16, v88
	v_and_b32_e32 v201, 0xffff0000, v88
	v_lshlrev_b32_e32 v202, 16, v89
	v_and_b32_e32 v203, 0xffff0000, v89
	v_lshlrev_b32_e32 v204, 16, v90
	v_and_b32_e32 v205, 0xffff0000, v90
	v_lshlrev_b32_e32 v206, 16, v91
	v_and_b32_e32 v207, 0xffff0000, v91
	s_waitcnt lgkmcnt(2)
	v_mfma_f32_16x16x32_bf16 v[200:203], v[184:187], v[80:83], v[200:203]
	v_mfma_f32_16x16x32_bf16 v[204:207], v[192:195], v[80:83], v[204:207]
	s_waitcnt lgkmcnt(0)
	v_mfma_f32_16x16x32_bf16 v[200:203], v[188:191], v[84:87], v[200:203]
	v_mfma_f32_16x16x32_bf16 v[204:207], v[196:199], v[84:87], v[204:207]
	s_nop 6
	v_cvt_pk_bf16_f32 v200, v200, v201
	v_cvt_pk_bf16_f32 v201, v202, v203
	v_cvt_pk_bf16_f32 v204, v204, v205
	v_cvt_pk_bf16_f32 v205, v206, v207
	global_store_dwordx2 v[182:183], v[200:201], off
	global_store_dwordx2 v[182:183], v[204:205], off offset:32
	v_lshl_add_u64 v[182:183], v[182:183], 0, s[8:9]
	s_waitcnt lgkmcnt(0)
	s_barrier
	ds_read_b128 v[184:187], v10
	ds_read_b128 v[192:195], v10 offset:2560
	ds_read_b128 v[188:191], v10 offset:64
	ds_read_b128 v[196:199], v10 offset:2624
	s_waitcnt vmcnt(18)
	v_lshlrev_b32_e32 v200, 16, v100
	v_and_b32_e32 v201, 0xffff0000, v100
	v_lshlrev_b32_e32 v202, 16, v101
	v_and_b32_e32 v203, 0xffff0000, v101
	v_lshlrev_b32_e32 v204, 16, v102
	v_and_b32_e32 v205, 0xffff0000, v102
	v_lshlrev_b32_e32 v206, 16, v103
	v_and_b32_e32 v207, 0xffff0000, v103
	s_waitcnt lgkmcnt(2)
	v_mfma_f32_16x16x32_bf16 v[200:203], v[184:187], v[92:95], v[200:203]
	v_mfma_f32_16x16x32_bf16 v[204:207], v[192:195], v[92:95], v[204:207]
	s_waitcnt lgkmcnt(0)
	v_mfma_f32_16x16x32_bf16 v[200:203], v[188:191], v[96:99], v[200:203]
	v_mfma_f32_16x16x32_bf16 v[204:207], v[196:199], v[96:99], v[204:207]
	s_nop 6
	v_cvt_pk_bf16_f32 v200, v200, v201
	v_cvt_pk_bf16_f32 v201, v202, v203
	v_cvt_pk_bf16_f32 v204, v204, v205
	v_cvt_pk_bf16_f32 v205, v206, v207
	global_store_dwordx2 v[182:183], v[200:201], off
	global_store_dwordx2 v[182:183], v[204:205], off offset:32
	v_lshl_add_u64 v[182:183], v[182:183], 0, s[8:9]
	s_waitcnt lgkmcnt(0)
	s_barrier
	ds_read_b128 v[184:187], v10 offset:5120
	ds_read_b128 v[192:195], v10 offset:7680
	ds_read_b128 v[188:191], v10 offset:5184
	ds_read_b128 v[196:199], v10 offset:7744
	s_waitcnt vmcnt(14)
	v_lshlrev_b32_e32 v200, 16, v112
	v_and_b32_e32 v201, 0xffff0000, v112
	v_lshlrev_b32_e32 v202, 16, v113
	v_and_b32_e32 v203, 0xffff0000, v113
	v_lshlrev_b32_e32 v204, 16, v114
	v_and_b32_e32 v205, 0xffff0000, v114
	v_lshlrev_b32_e32 v206, 16, v115
	v_and_b32_e32 v207, 0xffff0000, v115
	s_waitcnt lgkmcnt(2)
	v_mfma_f32_16x16x32_bf16 v[200:203], v[184:187], v[104:107], v[200:203]
	v_mfma_f32_16x16x32_bf16 v[204:207], v[192:195], v[104:107], v[204:207]
	s_waitcnt lgkmcnt(0)
	v_mfma_f32_16x16x32_bf16 v[200:203], v[188:191], v[108:111], v[200:203]
	v_mfma_f32_16x16x32_bf16 v[204:207], v[196:199], v[108:111], v[204:207]
	s_nop 6
	v_cvt_pk_bf16_f32 v200, v200, v201
	v_cvt_pk_bf16_f32 v201, v202, v203
	v_cvt_pk_bf16_f32 v204, v204, v205
	v_cvt_pk_bf16_f32 v205, v206, v207
	global_store_dwordx2 v[182:183], v[200:201], off
	global_store_dwordx2 v[182:183], v[204:205], off offset:32
	v_lshl_add_u64 v[182:183], v[182:183], 0, s[8:9]
	s_waitcnt lgkmcnt(0)
	s_barrier
	s_branch .Lsp_done
.Lsp_hrole:
	s_add_u32 s6, s96, s0
	s_addc_u32 s7, s97, 0
	v_lshl_add_u64 v[2:3], s[6:7], 0, v[14:15]
	s_add_u32 s6, s88, s0
	s_addc_u32 s7, s89, 0
	v_lshl_add_u64 v[6:7], s[6:7], 0, v[18:19]
	global_load_dwordx4 v[20:23], v[2:3], off
	global_load_dwordx4 v[24:27], v[2:3], off offset:1024
	global_load_dwordx2 v[28:29], v[6:7], off
	global_load_dwordx2 v[30:31], v[6:7], off offset:2048
	v_lshl_add_u64 v[2:3], v[2:3], 0, s[8:9]
	v_lshl_add_u64 v[6:7], v[6:7], 0, s[8:9]
	global_load_dwordx4 v[32:35], v[2:3], off
	global_load_dwordx4 v[36:39], v[2:3], off offset:1024
	global_load_dwordx2 v[40:41], v[6:7], off
	global_load_dwordx2 v[42:43], v[6:7], off offset:2048
	v_lshl_add_u64 v[2:3], v[2:3], 0, s[8:9]
	v_lshl_add_u64 v[6:7], v[6:7], 0, s[8:9]
	global_load_dwordx4 v[44:47], v[2:3], off
	global_load_dwordx4 v[48:51], v[2:3], off offset:1024
	global_load_dwordx2 v[52:53], v[6:7], off
	global_load_dwordx2 v[54:55], v[6:7], off offset:2048
	v_lshl_add_u64 v[2:3], v[2:3], 0, s[8:9]
	v_lshl_add_u64 v[6:7], v[6:7], 0, s[8:9]
	global_load_dwordx4 v[56:59], v[2:3], off
	global_load_dwordx4 v[60:63], v[2:3], off offset:1024
	global_load_dwordx2 v[64:65], v[6:7], off
	global_load_dwordx2 v[66:67], v[6:7], off offset:2048
	v_lshl_add_u64 v[2:3], v[2:3], 0, s[8:9]
	v_lshl_add_u64 v[6:7], v[6:7], 0, s[8:9]
	global_load_dwordx4 v[68:71], v[2:3], off
	global_load_dwordx4 v[72:75], v[2:3], off offset:1024
	global_load_dwordx2 v[76:77], v[6:7], off
	global_load_dwordx2 v[78:79], v[6:7], off offset:2048
	v_lshl_add_u64 v[2:3], v[2:3], 0, s[8:9]
	v_lshl_add_u64 v[6:7], v[6:7], 0, s[8:9]
	global_load_dwordx4 v[80:83], v[2:3], off
	global_load_dwordx4 v[84:87], v[2:3], off offset:1024
	global_load_dwordx2 v[88:89], v[6:7], off
	global_load_dwordx2 v[90:91], v[6:7], off offset:2048
	v_lshl_add_u64 v[2:3], v[2:3], 0, s[8:9]
	v_lshl_add_u64 v[6:7], v[6:7], 0, s[8:9]
	global_load_dwordx4 v[92:95], v[2:3], off
	global_load_dwordx4 v[96:99], v[2:3], off offset:1024
	global_load_dwordx2 v[100:101], v[6:7], off
	global_load_dwordx2 v[102:103], v[6:7], off offset:2048
	v_lshl_add_u64 v[2:3], v[2:3], 0, s[8:9]
	v_lshl_add_u64 v[6:7], v[6:7], 0, s[8:9]
	s_waitcnt lgkmcnt(0)
	s_barrier
	global_load_dwordx4 v[104:107], v[2:3], off
	global_load_dwordx4 v[108:111], v[2:3], off offset:1024
	global_load_dwordx2 v[112:113], v[6:7], off
	global_load_dwordx2 v[114:115], v[6:7], off offset:2048
	v_lshl_add_u64 v[2:3], v[2:3], 0, s[8:9]
	v_lshl_add_u64 v[6:7], v[6:7], 0, s[8:9]
	ds_read_b128 v[184:187], v10
	ds_read_b128 v[192:195], v10 offset:2560
	ds_read_b128 v[188:191], v10 offset:64
	ds_read_b128 v[196:199], v10 offset:2624
	s_waitcnt vmcnt(28)
	v_lshlrev_b32_e32 v200, 16, v28
	v_and_b32_e32 v201, 0xffff0000, v28
	v_lshlrev_b32_e32 v202, 16, v29
	v_and_b32_e32 v203, 0xffff0000, v29
	v_lshlrev_b32_e32 v204, 16, v30
	v_and_b32_e32 v205, 0xffff0000, v30
	v_lshlrev_b32_e32 v206, 16, v31
	v_and_b32_e32 v207, 0xffff0000, v31
	s_waitcnt lgkmcnt(2)
	v_mfma_f32_16x16x32_bf16 v[200:203], v[20:23], v[184:187], v[200:203]
	v_mfma_f32_16x16x32_bf16 v[204:207], v[20:23], v[192:195], v[204:207]
	s_waitcnt lgkmcnt(0)
	v_mfma_f32_16x16x32_bf16 v[200:203], v[24:27], v[188:191], v[200:203]
	v_mfma_f32_16x16x32_bf16 v[204:207], v[24:27], v[196:199], v[204:207]
	s_nop 6
	v_cvt_pk_bf16_f32 v200, v200, v201
	v_cvt_pk_bf16_f32 v201, v202, v203
	v_cvt_pk_bf16_f32 v204, v204, v205
	v_cvt_pk_bf16_f32 v205, v206, v207
	ds_write_b64 v11, v[200:201] offset:5120
	ds_write_b64 v11, v[204:205] offset:7680
	s_waitcnt lgkmcnt(0)
	s_barrier
	global_load_dwordx4 v[20:23], v[2:3], off
	global_load_dwordx4 v[24:27], v[2:3], off offset:1024
	global_load_dwordx2 v[28:29], v[6:7], off
	global_load_dwordx2 v[30:31], v[6:7], off offset:2048
	v_lshl_add_u64 v[2:3], v[2:3], 0, s[8:9]
	v_lshl_add_u64 v[6:7], v[6:7], 0, s[8:9]
	ds_read_b128 v[184:187], v10 offset:5120
	ds_read_b128 v[192:195], v10 offset:7680
	ds_read_b128 v[188:191], v10 offset:5184
	ds_read_b128 v[196:199], v10 offset:7744
	s_waitcnt vmcnt(28)
	v_lshlrev_b32_e32 v200, 16, v40
	v_and_b32_e32 v201, 0xffff0000, v40
	v_lshlrev_b32_e32 v202, 16, v41
	v_and_b32_e32 v203, 0xffff0000, v41
	v_lshlrev_b32_e32 v204, 16, v42
	v_and_b32_e32 v205, 0xffff0000, v42
	v_lshlrev_b32_e32 v206, 16, v43
	v_and_b32_e32 v207, 0xffff0000, v43
	s_waitcnt lgkmcnt(2)
	v_mfma_f32_16x16x32_bf16 v[200:203], v[32:35], v[184:187], v[200:203]
	v_mfma_f32_16x16x32_bf16 v[204:207], v[32:35], v[192:195], v[204:207]
	s_waitcnt lgkmcnt(0)
	v_mfma_f32_16x16x32_bf16 v[200:203], v[36:39], v[188:191], v[200:203]
	v_mfma_f32_16x16x32_bf16 v[204:207], v[36:39], v[196:199], v[204:207]
	s_nop 6
	v_cvt_pk_bf16_f32 v200, v200, v201
	v_cvt_pk_bf16_f32 v201, v202, v203
	v_cvt_pk_bf16_f32 v204, v204, v205
	v_cvt_pk_bf16_f32 v205, v206, v207
	ds_write_b64 v11, v[200:201]
	ds_write_b64 v11, v[204:205] offset:2560
	s_waitcnt lgkmcnt(0)
	s_barrier
	global_load_dwordx4 v[32:35], v[2:3], off
	global_load_dwordx4 v[36:39], v[2:3], off offset:1024
	global_load_dwordx2 v[40:41], v[6:7], off
	global_load_dwordx2 v[42:43], v[6:7], off offset:2048
	v_lshl_add_u64 v[2:3], v[2:3], 0, s[8:9]
	v_lshl_add_u64 v[6:7], v[6:7], 0, s[8:9]
	ds_read_b128 v[184:187], v10
	ds_read_b128 v[192:195], v10 offset:2560
	ds_read_b128 v[188:191], v10 offset:64
	ds_read_b128 v[196:199], v10 offset:2624
	s_waitcnt vmcnt(28)
	v_lshlrev_b32_e32 v200, 16, v52
	v_and_b32_e32 v201, 0xffff0000, v52
	v_lshlrev_b32_e32 v202, 16, v53
	v_and_b32_e32 v203, 0xffff0000, v53
	v_lshlrev_b32_e32 v204, 16, v54
	v_and_b32_e32 v205, 0xffff0000, v54
	v_lshlrev_b32_e32 v206, 16, v55
	v_and_b32_e32 v207, 0xffff0000, v55
	s_waitcnt lgkmcnt(2)
	v_mfma_f32_16x16x32_bf16 v[200:203], v[44:47], v[184:187], v[200:203]
	v_mfma_f32_16x16x32_bf16 v[204:207], v[44:47], v[192:195], v[204:207]
	s_waitcnt lgkmcnt(0)
	v_mfma_f32_16x16x32_bf16 v[200:203], v[48:51], v[188:191], v[200:203]
	v_mfma_f32_16x16x32_bf16 v[204:207], v[48:51], v[196:199], v[204:207]
	s_nop 6
	v_cvt_pk_bf16_f32 v200, v200, v201
	v_cvt_pk_bf16_f32 v201, v202, v203
	v_cvt_pk_bf16_f32 v204, v204, v205
	v_cvt_pk_bf16_f32 v205, v206, v207
	ds_write_b64 v11, v[200:201] offset:5120
	ds_write_b64 v11, v[204:205] offset:7680
	s_waitcnt lgkmcnt(0)
	s_barrier
	global_load_dwordx4 v[44:47], v[2:3], off
	global_load_dwordx4 v[48:51], v[2:3], off offset:1024
	global_load_dwordx2 v[52:53], v[6:7], off
	global_load_dwordx2 v[54:55], v[6:7], off offset:2048
	v_lshl_add_u64 v[2:3], v[2:3], 0, s[8:9]
	v_lshl_add_u64 v[6:7], v[6:7], 0, s[8:9]
	ds_read_b128 v[184:187], v10 offset:5120
	ds_read_b128 v[192:195], v10 offset:7680
	ds_read_b128 v[188:191], v10 offset:5184
	ds_read_b128 v[196:199], v10 offset:7744
	s_waitcnt vmcnt(28)
	v_lshlrev_b32_e32 v200, 16, v64
	v_and_b32_e32 v201, 0xffff0000, v64
	v_lshlrev_b32_e32 v202, 16, v65
	v_and_b32_e32 v203, 0xffff0000, v65
	v_lshlrev_b32_e32 v204, 16, v66
	v_and_b32_e32 v205, 0xffff0000, v66
	v_lshlrev_b32_e32 v206, 16, v67
	v_and_b32_e32 v207, 0xffff0000, v67
	s_waitcnt lgkmcnt(2)
	v_mfma_f32_16x16x32_bf16 v[200:203], v[56:59], v[184:187], v[200:203]
	v_mfma_f32_16x16x32_bf16 v[204:207], v[56:59], v[192:195], v[204:207]
	s_waitcnt lgkmcnt(0)
	v_mfma_f32_16x16x32_bf16 v[200:203], v[60:63], v[188:191], v[200:203]
	v_mfma_f32_16x16x32_bf16 v[204:207], v[60:63], v[196:199], v[204:207]
	s_nop 6
	v_cvt_pk_bf16_f32 v200, v200, v201
	v_cvt_pk_bf16_f32 v201, v202, v203
	v_cvt_pk_bf16_f32 v204, v204, v205
	v_cvt_pk_bf16_f32 v205, v206, v207
	ds_write_b64 v11, v[200:201]
	ds_write_b64 v11, v[204:205] offset:2560
	s_waitcnt lgkmcnt(0)
	s_barrier
	global_load_dwordx4 v[56:59], v[2:3], off
	global_load_dwordx4 v[60:63], v[2:3], off offset:1024
	global_load_dwordx2 v[64:65], v[6:7], off
	global_load_dwordx2 v[66:67], v[6:7], off offset:2048
	v_lshl_add_u64 v[2:3], v[2:3], 0, s[8:9]
	v_lshl_add_u64 v[6:7], v[6:7], 0, s[8:9]
	ds_read_b128 v[184:187], v10
	ds_read_b128 v[192:195], v10 offset:2560
	ds_read_b128 v[188:191], v10 offset:64
	ds_read_b128 v[196:199], v10 offset:2624
	s_waitcnt vmcnt(28)
	v_lshlrev_b32_e32 v200, 16, v76
	v_and_b32_e32 v201, 0xffff0000, v76
	v_lshlrev_b32_e32 v202, 16, v77
	v_and_b32_e32 v203, 0xffff0000, v77
	v_lshlrev_b32_e32 v204, 16, v78
	v_and_b32_e32 v205, 0xffff0000, v78
	v_lshlrev_b32_e32 v206, 16, v79
	v_and_b32_e32 v207, 0xffff0000, v79
	s_waitcnt lgkmcnt(2)
	v_mfma_f32_16x16x32_bf16 v[200:203], v[68:71], v[184:187], v[200:203]
	v_mfma_f32_16x16x32_bf16 v[204:207], v[68:71], v[192:195], v[204:207]
	s_waitcnt lgkmcnt(0)
	v_mfma_f32_16x16x32_bf16 v[200:203], v[72:75], v[188:191], v[200:203]
	v_mfma_f32_16x16x32_bf16 v[204:207], v[72:75], v[196:199], v[204:207]
	s_nop 6
	v_cvt_pk_bf16_f32 v200, v200, v201
	v_cvt_pk_bf16_f32 v201, v202, v203
	v_cvt_pk_bf16_f32 v204, v204, v205
	v_cvt_pk_bf16_f32 v205, v206, v207
	ds_write_b64 v11, v[200:201] offset:5120
	ds_write_b64 v11, v[204:205] offset:7680
	s_waitcnt lgkmcnt(0)
	s_barrier
	global_load_dwordx4 v[68:71], v[2:3], off
	global_load_dwordx4 v[72:75], v[2:3], off offset:1024
	global_load_dwordx2 v[76:77], v[6:7], off
	global_load_dwordx2 v[78:79], v[6:7], off offset:2048
	v_lshl_add_u64 v[2:3], v[2:3], 0, s[8:9]
	v_lshl_add_u64 v[6:7], v[6:7], 0, s[8:9]
	ds_read_b128 v[184:187], v10 offset:5120
	ds_read_b128 v[192:195], v10 offset:7680
	ds_read_b128 v[188:191], v10 offset:5184
	ds_read_b128 v[196:199], v10 offset:7744
	s_waitcnt vmcnt(28)
	v_lshlrev_b32_e32 v200, 16, v88
	v_and_b32_e32 v201, 0xffff0000, v88
	v_lshlrev_b32_e32 v202, 16, v89
	v_and_b32_e32 v203, 0xffff0000, v89
	v_lshlrev_b32_e32 v204, 16, v90
	v_and_b32_e32 v205, 0xffff0000, v90
	v_lshlrev_b32_e32 v206, 16, v91
	v_and_b32_e32 v207, 0xffff0000, v91
	s_waitcnt lgkmcnt(2)
	v_mfma_f32_16x16x32_bf16 v[200:203], v[80:83], v[184:187], v[200:203]
	v_mfma_f32_16x16x32_bf16 v[204:207], v[80:83], v[192:195], v[204:207]
	s_waitcnt lgkmcnt(0)
	v_mfma_f32_16x16x32_bf16 v[200:203], v[84:87], v[188:191], v[200:203]
	v_mfma_f32_16x16x32_bf16 v[204:207], v[84:87], v[196:199], v[204:207]
	s_nop 6
	v_cvt_pk_bf16_f32 v200, v200, v201
	v_cvt_pk_bf16_f32 v201, v202, v203
	v_cvt_pk_bf16_f32 v204, v204, v205
	v_cvt_pk_bf16_f32 v205, v206, v207
	ds_write_b64 v11, v[200:201]
	ds_write_b64 v11, v[204:205] offset:2560
	s_waitcnt lgkmcnt(0)
	s_barrier
	global_load_dwordx4 v[80:83], v[2:3], off
	global_load_dwordx4 v[84:87], v[2:3], off offset:1024
	global_load_dwordx2 v[88:89], v[6:7], off
	global_load_dwordx2 v[90:91], v[6:7], off offset:2048
	v_lshl_add_u64 v[2:3], v[2:3], 0, s[8:9]
	v_lshl_add_u64 v[6:7], v[6:7], 0, s[8:9]
	ds_read_b128 v[184:187], v10
	ds_read_b128 v[192:195], v10 offset:2560
	ds_read_b128 v[188:191], v10 offset:64
	ds_read_b128 v[196:199], v10 offset:2624
	s_waitcnt vmcnt(28)
	v_lshlrev_b32_e32 v200, 16, v100
	v_and_b32_e32 v201, 0xffff0000, v100
	v_lshlrev_b32_e32 v202, 16, v101
	v_and_b32_e32 v203, 0xffff0000, v101
	v_lshlrev_b32_e32 v204, 16, v102
	v_and_b32_e32 v205, 0xffff0000, v102
	v_lshlrev_b32_e32 v206, 16, v103
	v_and_b32_e32 v207, 0xffff0000, v103
	s_waitcnt lgkmcnt(2)
	v_mfma_f32_16x16x32_bf16 v[200:203], v[92:95], v[184:187], v[200:203]
	v_mfma_f32_16x16x32_bf16 v[204:207], v[92:95], v[192:195], v[204:207]
	s_waitcnt lgkmcnt(0)
	v_mfma_f32_16x16x32_bf16 v[200:203], v[96:99], v[188:191], v[200:203]
	v_mfma_f32_16x16x32_bf16 v[204:207], v[96:99], v[196:199], v[204:207]
	s_nop 6
	v_cvt_pk_bf16_f32 v200, v200, v201
	v_cvt_pk_bf16_f32 v201, v202, v203
	v_cvt_pk_bf16_f32 v204, v204, v205
	v_cvt_pk_bf16_f32 v205, v206, v207
	ds_write_b64 v11, v[200:201] offset:5120
	ds_write_b64 v11, v[204:205] offset:7680
	s_waitcnt lgkmcnt(0)
	s_barrier
	global_load_dwordx4 v[92:95], v[2:3], off
	global_load_dwordx4 v[96:99], v[2:3], off offset:1024
	global_load_dwordx2 v[100:101], v[6:7], off
	global_load_dwordx2 v[102:103], v[6:7], off offset:2048
	v_lshl_add_u64 v[2:3], v[2:3], 0, s[8:9]
	v_lshl_add_u64 v[6:7], v[6:7], 0, s[8:9]
	ds_read_b128 v[184:187], v10 offset:5120
	ds_read_b128 v[192:195], v10 offset:7680
	ds_read_b128 v[188:191], v10 offset:5184
	ds_read_b128 v[196:199], v10 offset:7744
	s_waitcnt vmcnt(28)
	v_lshlrev_b32_e32 v200, 16, v112
	v_and_b32_e32 v201, 0xffff0000, v112
	v_lshlrev_b32_e32 v202, 16, v113
	v_and_b32_e32 v203, 0xffff0000, v113
	v_lshlrev_b32_e32 v204, 16, v114
	v_and_b32_e32 v205, 0xffff0000, v114
	v_lshlrev_b32_e32 v206, 16, v115
	v_and_b32_e32 v207, 0xffff0000, v115
	s_waitcnt lgkmcnt(2)
	v_mfma_f32_16x16x32_bf16 v[200:203], v[104:107], v[184:187], v[200:203]
	v_mfma_f32_16x16x32_bf16 v[204:207], v[104:107], v[192:195], v[204:207]
	s_waitcnt lgkmcnt(0)
	v_mfma_f32_16x16x32_bf16 v[200:203], v[108:111], v[188:191], v[200:203]
	v_mfma_f32_16x16x32_bf16 v[204:207], v[108:111], v[196:199], v[204:207]
	s_nop 6
	v_cvt_pk_bf16_f32 v200, v200, v201
	v_cvt_pk_bf16_f32 v201, v202, v203
	v_cvt_pk_bf16_f32 v204, v204, v205
	v_cvt_pk_bf16_f32 v205, v206, v207
	ds_write_b64 v11, v[200:201]
	ds_write_b64 v11, v[204:205] offset:2560
	s_waitcnt lgkmcnt(0)
	s_barrier
	s_mov_b32 s10, 6
.Lsp_loop1:
	global_load_dwordx4 v[104:107], v[2:3], off
	global_load_dwordx4 v[108:111], v[2:3], off offset:1024
	global_load_dwordx2 v[112:113], v[6:7], off
	global_load_dwordx2 v[114:115], v[6:7], off offset:2048
	v_lshl_add_u64 v[2:3], v[2:3], 0, s[8:9]
	v_lshl_add_u64 v[6:7], v[6:7], 0, s[8:9]
	ds_read_b128 v[184:187], v10
	ds_read_b128 v[192:195], v10 offset:2560
	ds_read_b128 v[188:191], v10 offset:64
	ds_read_b128 v[196:199], v10 offset:2624
	s_waitcnt vmcnt(28)
	v_lshlrev_b32_e32 v200, 16, v28
	v_and_b32_e32 v201, 0xffff0000, v28
	v_lshlrev_b32_e32 v202, 16, v29
	v_and_b32_e32 v203, 0xffff0000, v29
	v_lshlrev_b32_e32 v204, 16, v30
	v_and_b32_e32 v205, 0xffff0000, v30
	v_lshlrev_b32_e32 v206, 16, v31
	v_and_b32_e32 v207, 0xffff0000, v31
	s_waitcnt lgkmcnt(2)
	v_mfma_f32_16x16x32_bf16 v[200:203], v[20:23], v[184:187], v[200:203]
	v_mfma_f32_16x16x32_bf16 v[204:207], v[20:23], v[192:195], v[204:207]
	s_waitcnt lgkmcnt(0)
	v_mfma_f32_16x16x32_bf16 v[200:203], v[24:27], v[188:191], v[200:203]
	v_mfma_f32_16x16x32_bf16 v[204:207], v[24:27], v[196:199], v[204:207]
	s_nop 6
	v_cvt_pk_bf16_f32 v200, v200, v201
	v_cvt_pk_bf16_f32 v201, v202, v203
	v_cvt_pk_bf16_f32 v204, v204, v205
	v_cvt_pk_bf16_f32 v205, v206, v207
	ds_write_b64 v11, v[200:201] offset:5120
	ds_write_b64 v11, v[204:205] offset:7680
	s_waitcnt lgkmcnt(0)
	s_barrier
	global_load_dwordx4 v[20:23], v[2:3], off
	global_load_dwordx4 v[24:27], v[2:3], off offset:1024
	global_load_dwordx2 v[28:29], v[6:7], off
	global_load_dwordx2 v[30:31], v[6:7], off offset:2048
	v_lshl_add_u64 v[2:3], v[2:3], 0, s[8:9]
	v_lshl_add_u64 v[6:7], v[6:7], 0, s[8:9]
	ds_read_b128 v[184:187], v10 offset:5120
	ds_read_b128 v[192:195], v10 offset:7680
	ds_read_b128 v[188:191], v10 offset:5184
	ds_read_b128 v[196:199], v10 offset:7744
	s_waitcnt vmcnt(28)
	v_lshlrev_b32_e32 v200, 16, v40
	v_and_b32_e32 v201, 0xffff0000, v40
	v_lshlrev_b32_e32 v202, 16, v41
	v_and_b32_e32 v203, 0xffff0000, v41
	v_lshlrev_b32_e32 v204, 16, v42
	v_and_b32_e32 v205, 0xffff0000, v42
	v_lshlrev_b32_e32 v206, 16, v43
	v_and_b32_e32 v207, 0xffff0000, v43
	s_waitcnt lgkmcnt(2)
	v_mfma_f32_16x16x32_bf16 v[200:203], v[32:35], v[184:187], v[200:203]
	v_mfma_f32_16x16x32_bf16 v[204:207], v[32:35], v[192:195], v[204:207]
	s_waitcnt lgkmcnt(0)
	v_mfma_f32_16x16x32_bf16 v[200:203], v[36:39], v[188:191], v[200:203]
	v_mfma_f32_16x16x32_bf16 v[204:207], v[36:39], v[196:199], v[204:207]
	s_nop 6
	v_cvt_pk_bf16_f32 v200, v200, v201
	v_cvt_pk_bf16_f32 v201, v202, v203
	v_cvt_pk_bf16_f32 v204, v204, v205
	v_cvt_pk_bf16_f32 v205, v206, v207
	ds_write_b64 v11, v[200:201]
	ds_write_b64 v11, v[204:205] offset:2560
	s_waitcnt lgkmcnt(0)
	s_barrier
	global_load_dwordx4 v[32:35], v[2:3], off
	global_load_dwordx4 v[36:39], v[2:3], off offset:1024
	global_load_dwordx2 v[40:41], v[6:7], off
	global_load_dwordx2 v[42:43], v[6:7], off offset:2048
	v_lshl_add_u64 v[2:3], v[2:3], 0, s[8:9]
	v_lshl_add_u64 v[6:7], v[6:7], 0, s[8:9]
	ds_read_b128 v[184:187], v10
	ds_read_b128 v[192:195], v10 offset:2560
	ds_read_b128 v[188:191], v10 offset:64
	ds_read_b128 v[196:199], v10 offset:2624
	s_waitcnt vmcnt(28)
	v_lshlrev_b32_e32 v200, 16, v52
	v_and_b32_e32 v201, 0xffff0000, v52
	v_lshlrev_b32_e32 v202, 16, v53
	v_and_b32_e32 v203, 0xffff0000, v53
	v_lshlrev_b32_e32 v204, 16, v54
	v_and_b32_e32 v205, 0xffff0000, v54
	v_lshlrev_b32_e32 v206, 16, v55
	v_and_b32_e32 v207, 0xffff0000, v55
	s_waitcnt lgkmcnt(2)
	v_mfma_f32_16x16x32_bf16 v[200:203], v[44:47], v[184:187], v[200:203]
	v_mfma_f32_16x16x32_bf16 v[204:207], v[44:47], v[192:195], v[204:207]
	s_waitcnt lgkmcnt(0)
	v_mfma_f32_16x16x32_bf16 v[200:203], v[48:51], v[188:191], v[200:203]
	v_mfma_f32_16x16x32_bf16 v[204:207], v[48:51], v[196:199], v[204:207]
	s_nop 6
	v_cvt_pk_bf16_f32 v200, v200, v201
	v_cvt_pk_bf16_f32 v201, v202, v203
	v_cvt_pk_bf16_f32 v204, v204, v205
	v_cvt_pk_bf16_f32 v205, v206, v207
	ds_write_b64 v11, v[200:201] offset:5120
	ds_write_b64 v11, v[204:205] offset:7680
	s_waitcnt lgkmcnt(0)
	s_barrier
	global_load_dwordx4 v[44:47], v[2:3], off
	global_load_dwordx4 v[48:51], v[2:3], off offset:1024
	global_load_dwordx2 v[52:53], v[6:7], off
	global_load_dwordx2 v[54:55], v[6:7], off offset:2048
	v_lshl_add_u64 v[2:3], v[2:3], 0, s[8:9]
	v_lshl_add_u64 v[6:7], v[6:7], 0, s[8:9]
	ds_read_b128 v[184:187], v10 offset:5120
	ds_read_b128 v[192:195], v10 offset:7680
	ds_read_b128 v[188:191], v10 offset:5184
	ds_read_b128 v[196:199], v10 offset:7744
	s_waitcnt vmcnt(28)
	v_lshlrev_b32_e32 v200, 16, v64
	v_and_b32_e32 v201, 0xffff0000, v64
	v_lshlrev_b32_e32 v202, 16, v65
	v_and_b32_e32 v203, 0xffff0000, v65
	v_lshlrev_b32_e32 v204, 16, v66
	v_and_b32_e32 v205, 0xffff0000, v66
	v_lshlrev_b32_e32 v206, 16, v67
	v_and_b32_e32 v207, 0xffff0000, v67
	s_waitcnt lgkmcnt(2)
	v_mfma_f32_16x16x32_bf16 v[200:203], v[56:59], v[184:187], v[200:203]
	v_mfma_f32_16x16x32_bf16 v[204:207], v[56:59], v[192:195], v[204:207]
	s_waitcnt lgkmcnt(0)
	v_mfma_f32_16x16x32_bf16 v[200:203], v[60:63], v[188:191], v[200:203]
	v_mfma_f32_16x16x32_bf16 v[204:207], v[60:63], v[196:199], v[204:207]
	s_nop 6
	v_cvt_pk_bf16_f32 v200, v200, v201
	v_cvt_pk_bf16_f32 v201, v202, v203
	v_cvt_pk_bf16_f32 v204, v204, v205
	v_cvt_pk_bf16_f32 v205, v206, v207
	ds_write_b64 v11, v[200:201]
	ds_write_b64 v11, v[204:205] offset:2560
	s_waitcnt lgkmcnt(0)
	s_barrier
	global_load_dwordx4 v[56:59], v[2:3], off
	global_load_dwordx4 v[60:63], v[2:3], off offset:1024
	global_load_dwordx2 v[64:65], v[6:7], off
	global_load_dwordx2 v[66:67], v[6:7], off offset:2048
	v_lshl_add_u64 v[2:3], v[2:3], 0, s[8:9]
	v_lshl_add_u64 v[6:7], v[6:7], 0, s[8:9]
	ds_read_b128 v[184:187], v10
	ds_read_b128 v[192:195], v10 offset:2560
	ds_read_b128 v[188:191], v10 offset:64
	ds_read_b128 v[196:199], v10 offset:2624
	s_waitcnt vmcnt(28)
	v_lshlrev_b32_e32 v200, 16, v76
	v_and_b32_e32 v201, 0xffff0000, v76
	v_lshlrev_b32_e32 v202, 16, v77
	v_and_b32_e32 v203, 0xffff0000, v77
	v_lshlrev_b32_e32 v204, 16, v78
	v_and_b32_e32 v205, 0xffff0000, v78
	v_lshlrev_b32_e32 v206, 16, v79
	v_and_b32_e32 v207, 0xffff0000, v79
	s_waitcnt lgkmcnt(2)
	v_mfma_f32_16x16x32_bf16 v[200:203], v[68:71], v[184:187], v[200:203]
	v_mfma_f32_16x16x32_bf16 v[204:207], v[68:71], v[192:195], v[204:207]
	s_waitcnt lgkmcnt(0)
	v_mfma_f32_16x16x32_bf16 v[200:203], v[72:75], v[188:191], v[200:203]
	v_mfma_f32_16x16x32_bf16 v[204:207], v[72:75], v[196:199], v[204:207]
	s_nop 6
	v_cvt_pk_bf16_f32 v200, v200, v201
	v_cvt_pk_bf16_f32 v201, v202, v203
	v_cvt_pk_bf16_f32 v204, v204, v205
	v_cvt_pk_bf16_f32 v205, v206, v207
	ds_write_b64 v11, v[200:201] offset:5120
	ds_write_b64 v11, v[204:205] offset:7680
	s_waitcnt lgkmcnt(0)
	s_barrier
	global_load_dwordx4 v[68:71], v[2:3], off
	global_load_dwordx4 v[72:75], v[2:3], off offset:1024
	global_load_dwordx2 v[76:77], v[6:7], off
	global_load_dwordx2 v[78:79], v[6:7], off offset:2048
	v_lshl_add_u64 v[2:3], v[2:3], 0, s[8:9]
	v_lshl_add_u64 v[6:7], v[6:7], 0, s[8:9]
	ds_read_b128 v[184:187], v10 offset:5120
	ds_read_b128 v[192:195], v10 offset:7680
	ds_read_b128 v[188:191], v10 offset:5184
	ds_read_b128 v[196:199], v10 offset:7744
	s_waitcnt vmcnt(28)
	v_lshlrev_b32_e32 v200, 16, v88
	v_and_b32_e32 v201, 0xffff0000, v88
	v_lshlrev_b32_e32 v202, 16, v89
	v_and_b32_e32 v203, 0xffff0000, v89
	v_lshlrev_b32_e32 v204, 16, v90
	v_and_b32_e32 v205, 0xffff0000, v90
	v_lshlrev_b32_e32 v206, 16, v91
	v_and_b32_e32 v207, 0xffff0000, v91
	s_waitcnt lgkmcnt(2)
	v_mfma_f32_16x16x32_bf16 v[200:203], v[80:83], v[184:187], v[200:203]
	v_mfma_f32_16x16x32_bf16 v[204:207], v[80:83], v[192:195], v[204:207]
	s_waitcnt lgkmcnt(0)
	v_mfma_f32_16x16x32_bf16 v[200:203], v[84:87], v[188:191], v[200:203]
	v_mfma_f32_16x16x32_bf16 v[204:207], v[84:87], v[196:199], v[204:207]
	s_nop 6
	v_cvt_pk_bf16_f32 v200, v200, v201
	v_cvt_pk_bf16_f32 v201, v202, v203
	v_cvt_pk_bf16_f32 v204, v204, v205
	v_cvt_pk_bf16_f32 v205, v206, v207
	ds_write_b64 v11, v[200:201]
	ds_write_b64 v11, v[204:205] offset:2560
	s_waitcnt lgkmcnt(0)
	s_barrier
	global_load_dwordx4 v[80:83], v[2:3], off
	global_load_dwordx4 v[84:87], v[2:3], off offset:1024
	global_load_dwordx2 v[88:89], v[6:7], off
	global_load_dwordx2 v[90:91], v[6:7], off offset:2048
	v_lshl_add_u64 v[2:3], v[2:3], 0, s[8:9]
	v_lshl_add_u64 v[6:7], v[6:7], 0, s[8:9]
	ds_read_b128 v[184:187], v10
	ds_read_b128 v[192:195], v10 offset:2560
	ds_read_b128 v[188:191], v10 offset:64
	ds_read_b128 v[196:199], v10 offset:2624
	s_waitcnt vmcnt(28)
	v_lshlrev_b32_e32 v200, 16, v100
	v_and_b32_e32 v201, 0xffff0000, v100
	v_lshlrev_b32_e32 v202, 16, v101
	v_and_b32_e32 v203, 0xffff0000, v101
	v_lshlrev_b32_e32 v204, 16, v102
	v_and_b32_e32 v205, 0xffff0000, v102
	v_lshlrev_b32_e32 v206, 16, v103
	v_and_b32_e32 v207, 0xffff0000, v103
	s_waitcnt lgkmcnt(2)
	v_mfma_f32_16x16x32_bf16 v[200:203], v[92:95], v[184:187], v[200:203]
	v_mfma_f32_16x16x32_bf16 v[204:207], v[92:95], v[192:195], v[204:207]
	s_waitcnt lgkmcnt(0)
	v_mfma_f32_16x16x32_bf16 v[200:203], v[96:99], v[188:191], v[200:203]
	v_mfma_f32_16x16x32_bf16 v[204:207], v[96:99], v[196:199], v[204:207]
	s_nop 6
	v_cvt_pk_bf16_f32 v200, v200, v201
	v_cvt_pk_bf16_f32 v201, v202, v203
	v_cvt_pk_bf16_f32 v204, v204, v205
	v_cvt_pk_bf16_f32 v205, v206, v207
	ds_write_b64 v11, v[200:201] offset:5120
	ds_write_b64 v11, v[204:205] offset:7680
	s_waitcnt lgkmcnt(0)
	s_barrier
	global_load_dwordx4 v[92:95], v[2:3], off
	global_load_dwordx4 v[96:99], v[2:3], off offset:1024
	global_load_dwordx2 v[100:101], v[6:7], off
	global_load_dwordx2 v[102:103], v[6:7], off offset:2048
	v_lshl_add_u64 v[2:3], v[2:3], 0, s[8:9]
	v_lshl_add_u64 v[6:7], v[6:7], 0, s[8:9]
	ds_read_b128 v[184:187], v10 offset:5120
	ds_read_b128 v[192:195], v10 offset:7680
	ds_read_b128 v[188:191], v10 offset:5184
	ds_read_b128 v[196:199], v10 offset:7744
	s_waitcnt vmcnt(28)
	v_lshlrev_b32_e32 v200, 16, v112
	v_and_b32_e32 v201, 0xffff0000, v112
	v_lshlrev_b32_e32 v202, 16, v113
	v_and_b32_e32 v203, 0xffff0000, v113
	v_lshlrev_b32_e32 v204, 16, v114
	v_and_b32_e32 v205, 0xffff0000, v114
	v_lshlrev_b32_e32 v206, 16, v115
	v_and_b32_e32 v207, 0xffff0000, v115
	s_waitcnt lgkmcnt(2)
	v_mfma_f32_16x16x32_bf16 v[200:203], v[104:107], v[184:187], v[200:203]
	v_mfma_f32_16x16x32_bf16 v[204:207], v[104:107], v[192:195], v[204:207]
	s_waitcnt lgkmcnt(0)
	v_mfma_f32_16x16x32_bf16 v[200:203], v[108:111], v[188:191], v[200:203]
	v_mfma_f32_16x16x32_bf16 v[204:207], v[108:111], v[196:199], v[204:207]
	s_nop 6
	v_cvt_pk_bf16_f32 v200, v200, v201
	v_cvt_pk_bf16_f32 v201, v202, v203
	v_cvt_pk_bf16_f32 v204, v204, v205
	v_cvt_pk_bf16_f32 v205, v206, v207
	ds_write_b64 v11, v[200:201]
	ds_write_b64 v11, v[204:205] offset:2560
	s_waitcnt lgkmcnt(0)
	s_barrier
	s_add_i32 s10, s10, -1
	s_cmp_lg_u32 s10, 0
	s_cbranch_scc1 .Lsp_loop1
	global_load_dwordx4 v[104:107], v[2:3], off
	global_load_dwordx4 v[108:111], v[2:3], off offset:1024
	global_load_dwordx2 v[112:113], v[6:7], off
	global_load_dwordx2 v[114:115], v[6:7], off offset:2048
	v_lshl_add_u64 v[2:3], v[2:3], 0, s[8:9]
	v_lshl_add_u64 v[6:7], v[6:7], 0, s[8:9]
	ds_read_b128 v[184:187], v10
	ds_read_b128 v[192:195], v10 offset:2560
	ds_read_b128 v[188:191], v10 offset:64
	ds_read_b128 v[196:199], v10 offset:2624
	s_waitcnt vmcnt(28)
	v_lshlrev_b32_e32 v200, 16, v28
	v_and_b32_e32 v201, 0xffff0000, v28
	v_lshlrev_b32_e32 v202, 16, v29
	v_and_b32_e32 v203, 0xffff0000, v29
	v_lshlrev_b32_e32 v204, 16, v30
	v_and_b32_e32 v205, 0xffff0000, v30
	v_lshlrev_b32_e32 v206, 16, v31
	v_and_b32_e32 v207, 0xffff0000, v31
	s_waitcnt lgkmcnt(2)
	v_mfma_f32_16x16x32_bf16 v[200:203], v[20:23], v[184:187], v[200:203]
	v_mfma_f32_16x16x32_bf16 v[204:207], v[20:23], v[192:195], v[204:207]
	s_waitcnt lgkmcnt(0)
	v_mfma_f32_16x16x32_bf16 v[200:203], v[24:27], v[188:191], v[200:203]
	v_mfma_f32_16x16x32_bf16 v[204:207], v[24:27], v[196:199], v[204:207]
	s_nop 6
	v_cvt_pk_bf16_f32 v200, v200, v201
	v_cvt_pk_bf16_f32 v201, v202, v203
	v_cvt_pk_bf16_f32 v204, v204, v205
	v_cvt_pk_bf16_f32 v205, v206, v207
	ds_write_b64 v11, v[200:201] offset:5120
	ds_write_b64 v11, v[204:205] offset:7680
	s_waitcnt lgkmcnt(0)
	s_barrier
	ds_read_b128 v[184:187], v10 offset:5120
	ds_read_b128 v[192:195], v10 offset:7680
	ds_read_b128 v[188:191], v10 offset:5184
	ds_read_b128 v[196:199], v10 offset:7744
	s_waitcnt vmcnt(24)
	v_lshlrev_b32_e32 v200, 16, v40
	v_and_b32_e32 v201, 0xffff0000, v40
	v_lshlrev_b32_e32 v202, 16, v41
	v_and_b32_e32 v203, 0xffff0000, v41
	v_lshlrev_b32_e32 v204, 16, v42
	v_and_b32_e32 v205, 0xffff0000, v42
	v_lshlrev_b32_e32 v206, 16, v43
	v_and_b32_e32 v207, 0xffff0000, v43
	s_waitcnt lgkmcnt(2)
	v_mfma_f32_16x16x32_bf16 v[200:203], v[32:35], v[184:187], v[200:203]
	v_mfma_f32_16x16x32_bf16 v[204:207], v[32:35], v[192:195], v[204:207]
	s_waitcnt lgkmcnt(0)
	v_mfma_f32_16x16x32_bf16 v[200:203], v[36:39], v[188:191], v[200:203]
	v_mfma_f32_16x16x32_bf16 v[204:207], v[36:39], v[196:199], v[204:207]
	s_nop 6
	v_cvt_pk_bf16_f32 v200, v200, v201
	v_cvt_pk_bf16_f32 v201, v202, v203
	v_cvt_pk_bf16_f32 v204, v204, v205
	v_cvt_pk_bf16_f32 v205, v206, v207
	ds_write_b64 v11, v[200:201]
	ds_write_b64 v11, v[204:205] offset:2560
	s_waitcnt lgkmcnt(0)
	s_barrier
	ds_read_b128 v[184:187], v10
	ds_read_b128 v[192:195], v10 offset:2560
	ds_read_b128 v[188:191], v10 offset:64
	ds_read_b128 v[196:199], v10 offset:2624
	s_waitcnt vmcnt(20)
	v_lshlrev_b32_e32 v200, 16, v52
	v_and_b32_e32 v201, 0xffff0000, v52
	v_lshlrev_b32_e32 v202, 16, v53
	v_and_b32_e32 v203, 0xffff0000, v53
	v_lshlrev_b32_e32 v204, 16, v54
	v_and_b32_e32 v205, 0xffff0000, v54
	v_lshlrev_b32_e32 v206, 16, v55
	v_and_b32_e32 v207, 0xffff0000, v55
	s_waitcnt lgkmcnt(2)
	v_mfma_f32_16x16x32_bf16 v[200:203], v[44:47], v[184:187], v[200:203]
	v_mfma_f32_16x16x32_bf16 v[204:207], v[44:47], v[192:195], v[204:207]
	s_waitcnt lgkmcnt(0)
	v_mfma_f32_16x16x32_bf16 v[200:203], v[48:51], v[188:191], v[200:203]
	v_mfma_f32_16x16x32_bf16 v[204:207], v[48:51], v[196:199], v[204:207]
	s_nop 6
	v_cvt_pk_bf16_f32 v200, v200, v201
	v_cvt_pk_bf16_f32 v201, v202, v203
	v_cvt_pk_bf16_f32 v204, v204, v205
	v_cvt_pk_bf16_f32 v205, v206, v207
	ds_write_b64 v11, v[200:201] offset:5120
	ds_write_b64 v11, v[204:205] offset:7680
	s_waitcnt lgkmcnt(0)
	s_barrier
	ds_read_b128 v[184:187], v10 offset:5120
	ds_read_b128 v[192:195], v10 offset:7680
	ds_read_b128 v[188:191], v10 offset:5184
	ds_read_b128 v[196:199], v10 offset:7744
	s_waitcnt vmcnt(16)
	v_lshlrev_b32_e32 v200, 16, v64
	v_and_b32_e32 v201, 0xffff0000, v64
	v_lshlrev_b32_e32 v202, 16, v65
	v_and_b32_e32 v203, 0xffff0000, v65
	v_lshlrev_b32_e32 v204, 16, v66
	v_and_b32_e32 v205, 0xffff0000, v66
	v_lshlrev_b32_e32 v206, 16, v67
	v_and_b32_e32 v207, 0xffff0000, v67
	s_waitcnt lgkmcnt(2)
	v_mfma_f32_16x16x32_bf16 v[200:203], v[56:59], v[184:187], v[200:203]
	v_mfma_f32_16x16x32_bf16 v[204:207], v[56:59], v[192:195], v[204:207]
	s_waitcnt lgkmcnt(0)
	v_mfma_f32_16x16x32_bf16 v[200:203], v[60:63], v[188:191], v[200:203]
	v_mfma_f32_16x16x32_bf16 v[204:207], v[60:63], v[196:199], v[204:207]
	s_nop 6
	v_cvt_pk_bf16_f32 v200, v200, v201
	v_cvt_pk_bf16_f32 v201, v202, v203
	v_cvt_pk_bf16_f32 v204, v204, v205
	v_cvt_pk_bf16_f32 v205, v206, v207
	ds_write_b64 v11, v[200:201]
	ds_write_b64 v11, v[204:205] offset:2560
	s_waitcnt lgkmcnt(0)
	s_barrier
	ds_read_b128 v[184:187], v10
	ds_read_b128 v[192:195], v10 offset:2560
	ds_read_b128 v[188:191], v10 offset:64
	ds_read_b128 v[196:199], v10 offset:2624
	s_waitcnt vmcnt(12)
	v_lshlrev_b32_e32 v200, 16, v76
	v_and_b32_e32 v201, 0xffff0000, v76
	v_lshlrev_b32_e32 v202, 16, v77
	v_and_b32_e32 v203, 0xffff0000, v77
	v_lshlrev_b32_e32 v204, 16, v78
	v_and_b32_e32 v205, 0xffff0000, v78
	v_lshlrev_b32_e32 v206, 16, v79
	v_and_b32_e32 v207, 0xffff0000, v79
	s_waitcnt lgkmcnt(2)
	v_mfma_f32_16x16x32_bf16 v[200:203], v[68:71], v[184:187], v[200:203]
	v_mfma_f32_16x16x32_bf16 v[204:207], v[68:71], v[192:195], v[204:207]
	s_waitcnt lgkmcnt(0)
	v_mfma_f32_16x16x32_bf16 v[200:203], v[72:75], v[188:191], v[200:203]
	v_mfma_f32_16x16x32_bf16 v[204:207], v[72:75], v[196:199], v[204:207]
	s_nop 6
	v_cvt_pk_bf16_f32 v200, v200, v201
	v_cvt_pk_bf16_f32 v201, v202, v203
	v_cvt_pk_bf16_f32 v204, v204, v205
	v_cvt_pk_bf16_f32 v205, v206, v207
	ds_write_b64 v11, v[200:201] offset:5120
	ds_write_b64 v11, v[204:205] offset:7680
	s_waitcnt lgkmcnt(0)
	s_barrier
	ds_read_b128 v[184:187], v10 offset:5120
	ds_read_b128 v[192:195], v10 offset:7680
	ds_read_b128 v[188:191], v10 offset:5184
	ds_read_b128 v[196:199], v10 offset:7744
	s_waitcnt vmcnt(8)
	v_lshlrev_b32_e32 v200, 16, v88
	v_and_b32_e32 v201, 0xffff0000, v88
	v_lshlrev_b32_e32 v202, 16, v89
	v_and_b32_e32 v203, 0xffff0000, v89
	v_lshlrev_b32_e32 v204, 16, v90
	v_and_b32_e32 v205, 0xffff0000, v90
	v_lshlrev_b32_e32 v206, 16, v91
	v_and_b32_e32 v207, 0xffff0000, v91
	s_waitcnt lgkmcnt(2)
	v_mfma_f32_16x16x32_bf16 v[200:203], v[80:83], v[184:187], v[200:203]
	v_mfma_f32_16x16x32_bf16 v[204:207], v[80:83], v[192:195], v[204:207]
	s_waitcnt lgkmcnt(0)
	v_mfma_f32_16x16x32_bf16 v[200:203], v[84:87], v[188:191], v[200:203]
	v_mfma_f32_16x16x32_bf16 v[204:207], v[84:87], v[196:199], v[204:207]
	s_nop 6
	v_cvt_pk_bf16_f32 v200, v200, v201
	v_cvt_pk_bf16_f32 v201, v202, v203
	v_cvt_pk_bf16_f32 v204, v204, v205
	v_cvt_pk_bf16_f32 v205, v206, v207
	ds_write_b64 v11, v[200:201]
	ds_write_b64 v11, v[204:205] offset:2560
	s_waitcnt lgkmcnt(0)
	s_barrier
	ds_read_b128 v[184:187], v10
	ds_read_b128 v[192:195], v10 offset:2560
	ds_read_b128 v[188:191], v10 offset:64
	ds_read_b128 v[196:199], v10 offset:2624
	s_waitcnt vmcnt(4)
	v_lshlrev_b32_e32 v200, 16, v100
	v_and_b32_e32 v201, 0xffff0000, v100
	v_lshlrev_b32_e32 v202, 16, v101
	v_and_b32_e32 v203, 0xffff0000, v101
	v_lshlrev_b32_e32 v204, 16, v102
	v_and_b32_e32 v205, 0xffff0000, v102
	v_lshlrev_b32_e32 v206, 16, v103
	v_and_b32_e32 v207, 0xffff0000, v103
	s_waitcnt lgkmcnt(2)
	v_mfma_f32_16x16x32_bf16 v[200:203], v[92:95], v[184:187], v[200:203]
	v_mfma_f32_16x16x32_bf16 v[204:207], v[92:95], v[192:195], v[204:207]
	s_waitcnt lgkmcnt(0)
	v_mfma_f32_16x16x32_bf16 v[200:203], v[96:99], v[188:191], v[200:203]
	v_mfma_f32_16x16x32_bf16 v[204:207], v[96:99], v[196:199], v[204:207]
	s_nop 6
	v_cvt_pk_bf16_f32 v200, v200, v201
	v_cvt_pk_bf16_f32 v201, v202, v203
	v_cvt_pk_bf16_f32 v204, v204, v205
	v_cvt_pk_bf16_f32 v205, v206, v207
	ds_write_b64 v11, v[200:201] offset:5120
	ds_write_b64 v11, v[204:205] offset:7680
	s_waitcnt lgkmcnt(0)
	s_barrier
	ds_read_b128 v[184:187], v10 offset:5120
	ds_read_b128 v[192:195], v10 offset:7680
	ds_read_b128 v[188:191], v10 offset:5184
	ds_read_b128 v[196:199], v10 offset:7744
	s_waitcnt vmcnt(0)
	v_lshlrev_b32_e32 v200, 16, v112
	v_and_b32_e32 v201, 0xffff0000, v112
	v_lshlrev_b32_e32 v202, 16, v113
	v_and_b32_e32 v203, 0xffff0000, v113
	v_lshlrev_b32_e32 v204, 16, v114
	v_and_b32_e32 v205, 0xffff0000, v114
	v_lshlrev_b32_e32 v206, 16, v115
	v_and_b32_e32 v207, 0xffff0000, v115
	s_waitcnt lgkmcnt(2)
	v_mfma_f32_16x16x32_bf16 v[200:203], v[104:107], v[184:187], v[200:203]
	v_mfma_f32_16x16x32_bf16 v[204:207], v[104:107], v[192:195], v[204:207]
	s_waitcnt lgkmcnt(0)
	v_mfma_f32_16x16x32_bf16 v[200:203], v[108:111], v[188:191], v[200:203]
	v_mfma_f32_16x16x32_bf16 v[204:207], v[108:111], v[196:199], v[204:207]
	s_nop 6
	v_cvt_pk_bf16_f32 v200, v200, v201
	v_cvt_pk_bf16_f32 v201, v202, v203
	v_cvt_pk_bf16_f32 v204, v204, v205
	v_cvt_pk_bf16_f32 v205, v206, v207
	ds_write_b64 v11, v[200:201]
	ds_write_b64 v11, v[204:205] offset:2560
	s_waitcnt lgkmcnt(0)
	s_barrier
.Lsp_done:
.LBB0_464:
	v_readlane_b32 s4, v250, 5
	v_readlane_b32 s5, v250, 6
	s_cmp_lt_i32 s5, 4
	s_cbranch_scc1 .LBB0_518
	s_waitcnt vmcnt(0)
	s_waitcnt lgkmcnt(0)
	s_barrier
	s_mov_b64 s[0:1], exec
	v_readlane_b32 s2, v250, 10
	v_readlane_b32 s3, v250, 11
	s_and_b64 s[2:3], s[0:1], s[2:3]
	s_mov_b64 exec, s[2:3]
	s_cbranch_execz .LBB0_517
	s_add_i32 s2, 0, 0x23160
	v_mov_b32_e32 v1, s2
	s_waitcnt vmcnt(0) expcnt(0) lgkmcnt(0)
	ds_read_b32 v3, v1
	s_add_i32 s2, 0, 0x23164
	v_mov_b32_e32 v1, s2
	ds_read_b32 v1, v1
	s_waitcnt lgkmcnt(1)
	v_cmp_ne_u32_e32 vcc, 0, v3
	s_cbranch_vccnz .LBB0_481
	v_readlane_b32 s2, v250, 0
	v_readlane_b32 s3, v250, 1
	s_load_dwordx2 s[6:7], s[2:3], 0x4
	s_add_u32 s2, s98, 0x4200
	s_addc_u32 s3, s99, 0
	s_add_u32 s4, s98, 0x4400
	s_addc_u32 s5, s99, 0
	v_readlane_b32 s8, v250, 4
	s_waitcnt lgkmcnt(0)
	s_mul_i32 s33, s6, s8
	s_add_u32 s6, s98, 0x4500
	s_mul_i32 s33, s33, s7
	s_addc_u32 s7, s99, 0
	s_add_u32 s8, s98, 0x4600
	s_addc_u32 s9, s99, 0
	s_add_u32 s10, s98, 0x4700
	s_addc_u32 s11, s99, 0
	s_add_u32 s12, s98, 0x4800
	s_addc_u32 s13, s99, 0
	s_add_u32 s14, s98, 0x4900
	s_addc_u32 s15, s99, 0
	s_add_u32 s16, s98, 0x4a00
	s_addc_u32 s17, s99, 0
	s_add_u32 s18, s98, 0x4b00
	s_addc_u32 s19, s99, 0
	s_add_u32 s20, s98, 0x4c00
	s_addc_u32 s21, s99, 0
	s_add_u32 s22, s98, 0x4d00
	s_addc_u32 s23, s99, 0
	s_add_u32 s24, s98, 0x4e00
	s_addc_u32 s25, s99, 0
	s_add_u32 s26, s98, 0x4f00
	s_addc_u32 s27, s99, 0
	s_add_u32 s28, s98, 0x5000
	s_addc_u32 s29, s99, 0
	s_add_u32 s30, s98, 0x5100
	s_addc_u32 s31, s99, 0
	s_add_u32 s34, s98, 0x5200
	s_addc_u32 s35, s99, 0
	s_add_u32 s36, s98, 0x5300
	s_addc_u32 s37, s99, 0
	s_mov_b32 s44, 1
	v_mov_b32_e32 v17, 0
	s_branch .LBB0_469
